# v14 + Hyena spec_mul as straight-line code: 4 elements (12 LDS reads) in flight with counted lgkmcnt waits instead of one element per loop trip
# speedup vs baseline: 1.0070x; 1.0070x over previous
.LBB0_433:
	v_add_u32_e32 v160, 0x11000, v155
	v_lshlrev_b32_e32 v161, 3, v154
	v_add_u32_e32 v161, 0x2200, v161
	v_add_u32_e32 v162, 0x11100, v156
	v_cmp_ne_u32_e32 vcc, 0, v32
	v_cndmask_b32_e32 v163, 0, v154, vcc
	v_lshlrev_b32_e32 v163, 3, v163
	v_add_u32_e32 v163, 0x11000, v163
	ds_read_b64 v[214:215], v160 offset:0
	ds_read_b64 v[216:217], v163
	ds_read_b64 v[218:219], v155 offset:0
	ds_read_b64 v[220:221], v160 offset:4352
	ds_read_b64 v[222:223], v162 offset:60928
	ds_read_b64 v[224:225], v155 offset:4352
	ds_read_b64 v[226:227], v160 offset:8704
	ds_read_b64 v[228:229], v161 offset:52224
	ds_read_b64 v[230:231], v155 offset:8704
	ds_read_b64 v[232:233], v160 offset:13056
	ds_read_b64 v[234:235], v162 offset:52224
	ds_read_b64 v[236:237], v155 offset:13056
	s_waitcnt lgkmcnt(9)
	v_add_f32_e32 v164, v214, v216
	v_mul_f32_e32 v214, 0.5, v164
	v_sub_f32_e32 v164, v215, v217
	v_mul_f32_e32 v216, 0.5, v164
	v_pk_mul_f32 v[216:217], v[218:219], v[216:217] op_sel:[1,0] op_sel_hi:[0,0]
	v_pk_fma_f32 v[158:159], v[218:219], v[214:215], v[216:217] neg_lo:[0,0,1] neg_hi:[0,0,1]
	v_pk_fma_f32 v[214:215], v[218:219], v[214:215], v[216:217] op_sel_hi:[1,0,1]
	s_nop 0
	v_mov_b32_e32 v159, v215
	v_pk_mul_f32 v[218:219], v[158:159], s[24:25]
	ds_write_b64 v155, v[218:219] offset:0
	s_waitcnt lgkmcnt(7)
	v_add_f32_e32 v164, v220, v222
	v_mul_f32_e32 v220, 0.5, v164
	v_sub_f32_e32 v164, v221, v223
	v_mul_f32_e32 v222, 0.5, v164
	v_pk_mul_f32 v[222:223], v[224:225], v[222:223] op_sel:[1,0] op_sel_hi:[0,0]
	v_pk_fma_f32 v[158:159], v[224:225], v[220:221], v[222:223] neg_lo:[0,0,1] neg_hi:[0,0,1]
	v_pk_fma_f32 v[220:221], v[224:225], v[220:221], v[222:223] op_sel_hi:[1,0,1]
	s_nop 0
	v_mov_b32_e32 v159, v221
	v_pk_mul_f32 v[224:225], v[158:159], s[24:25]
	ds_write_b64 v155, v[224:225] offset:4352
	s_waitcnt lgkmcnt(5)
	v_add_f32_e32 v164, v226, v228
	v_mul_f32_e32 v226, 0.5, v164
	v_sub_f32_e32 v164, v227, v229
	v_mul_f32_e32 v228, 0.5, v164
	v_pk_mul_f32 v[228:229], v[230:231], v[228:229] op_sel:[1,0] op_sel_hi:[0,0]
	v_pk_fma_f32 v[158:159], v[230:231], v[226:227], v[228:229] neg_lo:[0,0,1] neg_hi:[0,0,1]
	v_pk_fma_f32 v[226:227], v[230:231], v[226:227], v[228:229] op_sel_hi:[1,0,1]
	s_nop 0
	v_mov_b32_e32 v159, v227
	v_pk_mul_f32 v[230:231], v[158:159], s[24:25]
	ds_write_b64 v155, v[230:231] offset:8704
	s_waitcnt lgkmcnt(3)
	v_add_f32_e32 v164, v232, v234
	v_mul_f32_e32 v232, 0.5, v164
	v_sub_f32_e32 v164, v233, v235
	v_mul_f32_e32 v234, 0.5, v164
	v_pk_mul_f32 v[234:235], v[236:237], v[234:235] op_sel:[1,0] op_sel_hi:[0,0]
	v_pk_fma_f32 v[158:159], v[236:237], v[232:233], v[234:235] neg_lo:[0,0,1] neg_hi:[0,0,1]
	v_pk_fma_f32 v[232:233], v[236:237], v[232:233], v[234:235] op_sel_hi:[1,0,1]
	s_nop 0
	v_mov_b32_e32 v159, v233
	v_pk_mul_f32 v[236:237], v[158:159], s[24:25]
	ds_write_b64 v155, v[236:237] offset:13056
	ds_read_b64 v[182:183], v160 offset:17408
	ds_read_b64 v[184:185], v161 offset:43520
	ds_read_b64 v[186:187], v155 offset:17408
	ds_read_b64 v[188:189], v160 offset:21760
	ds_read_b64 v[190:191], v162 offset:43520
	ds_read_b64 v[192:193], v155 offset:21760
	ds_read_b64 v[194:195], v160 offset:26112
	ds_read_b64 v[196:197], v161 offset:34816
	ds_read_b64 v[198:199], v155 offset:26112
	ds_read_b64 v[200:201], v160 offset:30464
	ds_read_b64 v[202:203], v162 offset:34816
	ds_read_b64 v[238:239], v155 offset:30464
	s_waitcnt lgkmcnt(9)
	v_add_f32_e32 v164, v182, v184
	v_mul_f32_e32 v182, 0.5, v164
	v_sub_f32_e32 v164, v183, v185
	v_mul_f32_e32 v184, 0.5, v164
	v_pk_mul_f32 v[184:185], v[186:187], v[184:185] op_sel:[1,0] op_sel_hi:[0,0]
	v_pk_fma_f32 v[158:159], v[186:187], v[182:183], v[184:185] neg_lo:[0,0,1] neg_hi:[0,0,1]
	v_pk_fma_f32 v[182:183], v[186:187], v[182:183], v[184:185] op_sel_hi:[1,0,1]
	s_nop 0
	v_mov_b32_e32 v159, v183
	v_pk_mul_f32 v[186:187], v[158:159], s[24:25]
	ds_write_b64 v155, v[186:187] offset:17408
	s_waitcnt lgkmcnt(7)
	v_add_f32_e32 v164, v188, v190
	v_mul_f32_e32 v188, 0.5, v164
	v_sub_f32_e32 v164, v189, v191
	v_mul_f32_e32 v190, 0.5, v164
	v_pk_mul_f32 v[190:191], v[192:193], v[190:191] op_sel:[1,0] op_sel_hi:[0,0]
	v_pk_fma_f32 v[158:159], v[192:193], v[188:189], v[190:191] neg_lo:[0,0,1] neg_hi:[0,0,1]
	v_pk_fma_f32 v[188:189], v[192:193], v[188:189], v[190:191] op_sel_hi:[1,0,1]
	s_nop 0
	v_mov_b32_e32 v159, v189
	v_pk_mul_f32 v[192:193], v[158:159], s[24:25]
	ds_write_b64 v155, v[192:193] offset:21760
	s_waitcnt lgkmcnt(5)
	v_add_f32_e32 v164, v194, v196
	v_mul_f32_e32 v194, 0.5, v164
	v_sub_f32_e32 v164, v195, v197
	v_mul_f32_e32 v196, 0.5, v164
	v_pk_mul_f32 v[196:197], v[198:199], v[196:197] op_sel:[1,0] op_sel_hi:[0,0]
	v_pk_fma_f32 v[158:159], v[198:199], v[194:195], v[196:197] neg_lo:[0,0,1] neg_hi:[0,0,1]
	v_pk_fma_f32 v[194:195], v[198:199], v[194:195], v[196:197] op_sel_hi:[1,0,1]
	s_nop 0
	v_mov_b32_e32 v159, v195
	v_pk_mul_f32 v[198:199], v[158:159], s[24:25]
	ds_write_b64 v155, v[198:199] offset:26112
	s_waitcnt lgkmcnt(3)
	v_add_f32_e32 v164, v200, v202
	v_mul_f32_e32 v200, 0.5, v164
	v_sub_f32_e32 v164, v201, v203
	v_mul_f32_e32 v202, 0.5, v164
	v_pk_mul_f32 v[202:203], v[238:239], v[202:203] op_sel:[1,0] op_sel_hi:[0,0]
	v_pk_fma_f32 v[158:159], v[238:239], v[200:201], v[202:203] neg_lo:[0,0,1] neg_hi:[0,0,1]
	v_pk_fma_f32 v[200:201], v[238:239], v[200:201], v[202:203] op_sel_hi:[1,0,1]
	s_nop 0
	v_mov_b32_e32 v159, v201
	v_pk_mul_f32 v[238:239], v[158:159], s[24:25]
	ds_write_b64 v155, v[238:239] offset:30464
	ds_read_b64 v[214:215], v160 offset:34816
	ds_read_b64 v[216:217], v161 offset:26112
	ds_read_b64 v[218:219], v155 offset:34816
	ds_read_b64 v[220:221], v160 offset:39168
	ds_read_b64 v[222:223], v162 offset:26112
	ds_read_b64 v[224:225], v155 offset:39168
	ds_read_b64 v[226:227], v160 offset:43520
	ds_read_b64 v[228:229], v161 offset:17408
	ds_read_b64 v[230:231], v155 offset:43520
	ds_read_b64 v[232:233], v160 offset:47872
	ds_read_b64 v[234:235], v162 offset:17408
	ds_read_b64 v[236:237], v155 offset:47872
	s_waitcnt lgkmcnt(9)
	v_add_f32_e32 v164, v214, v216
	v_mul_f32_e32 v214, 0.5, v164
	v_sub_f32_e32 v164, v215, v217
	v_mul_f32_e32 v216, 0.5, v164
	v_pk_mul_f32 v[216:217], v[218:219], v[216:217] op_sel:[1,0] op_sel_hi:[0,0]
	v_pk_fma_f32 v[158:159], v[218:219], v[214:215], v[216:217] neg_lo:[0,0,1] neg_hi:[0,0,1]
	v_pk_fma_f32 v[214:215], v[218:219], v[214:215], v[216:217] op_sel_hi:[1,0,1]
	s_nop 0
	v_mov_b32_e32 v159, v215
	v_pk_mul_f32 v[218:219], v[158:159], s[24:25]
	ds_write_b64 v155, v[218:219] offset:34816
	s_waitcnt lgkmcnt(7)
	v_add_f32_e32 v164, v220, v222
	v_mul_f32_e32 v220, 0.5, v164
	v_sub_f32_e32 v164, v221, v223
	v_mul_f32_e32 v222, 0.5, v164
	v_pk_mul_f32 v[222:223], v[224:225], v[222:223] op_sel:[1,0] op_sel_hi:[0,0]
	v_pk_fma_f32 v[158:159], v[224:225], v[220:221], v[222:223] neg_lo:[0,0,1] neg_hi:[0,0,1]
	v_pk_fma_f32 v[220:221], v[224:225], v[220:221], v[222:223] op_sel_hi:[1,0,1]
	s_nop 0
	v_mov_b32_e32 v159, v221
	v_pk_mul_f32 v[224:225], v[158:159], s[24:25]
	ds_write_b64 v155, v[224:225] offset:39168
	s_waitcnt lgkmcnt(5)
	v_add_f32_e32 v164, v226, v228
	v_mul_f32_e32 v226, 0.5, v164
	v_sub_f32_e32 v164, v227, v229
	v_mul_f32_e32 v228, 0.5, v164
	v_pk_mul_f32 v[228:229], v[230:231], v[228:229] op_sel:[1,0] op_sel_hi:[0,0]
	v_pk_fma_f32 v[158:159], v[230:231], v[226:227], v[228:229] neg_lo:[0,0,1] neg_hi:[0,0,1]
	v_pk_fma_f32 v[226:227], v[230:231], v[226:227], v[228:229] op_sel_hi:[1,0,1]
	s_nop 0
	v_mov_b32_e32 v159, v227
	v_pk_mul_f32 v[230:231], v[158:159], s[24:25]
	ds_write_b64 v155, v[230:231] offset:43520
	s_waitcnt lgkmcnt(3)
	v_add_f32_e32 v164, v232, v234
	v_mul_f32_e32 v232, 0.5, v164
	v_sub_f32_e32 v164, v233, v235
	v_mul_f32_e32 v234, 0.5, v164
	v_pk_mul_f32 v[234:235], v[236:237], v[234:235] op_sel:[1,0] op_sel_hi:[0,0]
	v_pk_fma_f32 v[158:159], v[236:237], v[232:233], v[234:235] neg_lo:[0,0,1] neg_hi:[0,0,1]
	v_pk_fma_f32 v[232:233], v[236:237], v[232:233], v[234:235] op_sel_hi:[1,0,1]
	s_nop 0
	v_mov_b32_e32 v159, v233
	v_pk_mul_f32 v[236:237], v[158:159], s[24:25]
	ds_write_b64 v155, v[236:237] offset:47872
	ds_read_b64 v[182:183], v160 offset:52224
	ds_read_b64 v[184:185], v161 offset:8704
	ds_read_b64 v[186:187], v155 offset:52224
	ds_read_b64 v[188:189], v160 offset:56576
	ds_read_b64 v[190:191], v162 offset:8704
	ds_read_b64 v[192:193], v155 offset:56576
	ds_read_b64 v[194:195], v160 offset:60928
	ds_read_b64 v[196:197], v161 offset:0
	ds_read_b64 v[198:199], v155 offset:60928
	ds_read_b64 v[200:201], v160 offset:65280
	ds_read_b64 v[202:203], v162 offset:0
	ds_read_b64 v[238:239], v155 offset:65280
	s_waitcnt lgkmcnt(9)
	v_add_f32_e32 v164, v182, v184
	v_mul_f32_e32 v182, 0.5, v164
	v_sub_f32_e32 v164, v183, v185
	v_mul_f32_e32 v184, 0.5, v164
	v_pk_mul_f32 v[184:185], v[186:187], v[184:185] op_sel:[1,0] op_sel_hi:[0,0]
	v_pk_fma_f32 v[158:159], v[186:187], v[182:183], v[184:185] neg_lo:[0,0,1] neg_hi:[0,0,1]
	v_pk_fma_f32 v[182:183], v[186:187], v[182:183], v[184:185] op_sel_hi:[1,0,1]
	s_nop 0
	v_mov_b32_e32 v159, v183
	v_pk_mul_f32 v[186:187], v[158:159], s[24:25]
	ds_write_b64 v155, v[186:187] offset:52224
	s_waitcnt lgkmcnt(7)
	v_add_f32_e32 v164, v188, v190
	v_mul_f32_e32 v188, 0.5, v164
	v_sub_f32_e32 v164, v189, v191
	v_mul_f32_e32 v190, 0.5, v164
	v_pk_mul_f32 v[190:191], v[192:193], v[190:191] op_sel:[1,0] op_sel_hi:[0,0]
	v_pk_fma_f32 v[158:159], v[192:193], v[188:189], v[190:191] neg_lo:[0,0,1] neg_hi:[0,0,1]
	v_pk_fma_f32 v[188:189], v[192:193], v[188:189], v[190:191] op_sel_hi:[1,0,1]
	s_nop 0
	v_mov_b32_e32 v159, v189
	v_pk_mul_f32 v[192:193], v[158:159], s[24:25]
	ds_write_b64 v155, v[192:193] offset:56576
	s_waitcnt lgkmcnt(5)
	v_add_f32_e32 v164, v194, v196
	v_mul_f32_e32 v194, 0.5, v164
	v_sub_f32_e32 v164, v195, v197
	v_mul_f32_e32 v196, 0.5, v164
	v_pk_mul_f32 v[196:197], v[198:199], v[196:197] op_sel:[1,0] op_sel_hi:[0,0]
	v_pk_fma_f32 v[158:159], v[198:199], v[194:195], v[196:197] neg_lo:[0,0,1] neg_hi:[0,0,1]
	v_pk_fma_f32 v[194:195], v[198:199], v[194:195], v[196:197] op_sel_hi:[1,0,1]
	s_nop 0
	v_mov_b32_e32 v159, v195
	v_pk_mul_f32 v[198:199], v[158:159], s[24:25]
	ds_write_b64 v155, v[198:199] offset:60928
	s_waitcnt lgkmcnt(3)
	v_add_f32_e32 v164, v200, v202
	v_mul_f32_e32 v200, 0.5, v164
	v_sub_f32_e32 v164, v201, v203
	v_mul_f32_e32 v202, 0.5, v164
	v_pk_mul_f32 v[202:203], v[238:239], v[202:203] op_sel:[1,0] op_sel_hi:[0,0]
	v_pk_fma_f32 v[158:159], v[238:239], v[200:201], v[202:203] neg_lo:[0,0,1] neg_hi:[0,0,1]
	v_pk_fma_f32 v[200:201], v[238:239], v[200:201], v[202:203] op_sel_hi:[1,0,1]
	s_nop 0
	v_mov_b32_e32 v159, v201
	v_pk_mul_f32 v[238:239], v[158:159], s[24:25]
	ds_write_b64 v155, v[238:239] offset:65280
	s_mov_b32 s0, 16
	s_cmp_lg_u32 s0, 16
	s_waitcnt lgkmcnt(0)
	s_barrier
	s_and_saveexec_b64 s[0:1], s[40:41]
	s_cbranch_execz .LBB0_436
	ds_read_b64 v[0:1], v37 offset:2176
	ds_read_b64 v[2:3], v37 offset:4352
	ds_read_b64 v[4:5], v37 offset:6528
	ds_read_b64 v[6:7], v37 offset:8704
	ds_read_b64 v[8:9], v37 offset:10880
	ds_read_b64 v[10:11], v37 offset:13056
	ds_read_b64 v[12:13], v37 offset:15232
	ds_read_b64 v[14:15], v37 offset:17408
	ds_read_b64 v[16:17], v37 offset:19584
	ds_read_b64 v[18:19], v37 offset:21760
	ds_read_b64 v[20:21], v37 offset:23936
	ds_read_b64 v[22:23], v37 offset:26112
	ds_read_b64 v[24:25], v37 offset:34816
	ds_read_b64 v[26:27], v37 offset:36992
	ds_read_b64 v[28:29], v37 offset:39168
	ds_read_b64 v[30:31], v37 offset:41344
	ds_read_b64 v[102:103], v37 offset:43520
	ds_read_b64 v[110:111], v37 offset:45696
	ds_read_b64 v[118:119], v37 offset:47872
	ds_read_b64 v[120:121], v37 offset:50048
	ds_read_b64 v[122:123], v37 offset:52224
	ds_read_b64 v[124:125], v37 offset:54400
	ds_read_b64 v[126:127], v37 offset:56576
	ds_read_b64 v[128:129], v37 offset:58752
	ds_read_b64 v[130:131], v37
	ds_read_b64 v[132:133], v37 offset:60928
	ds_read_b64 v[134:135], v37 offset:63104
	ds_read_b64 v[136:137], v37 offset:65280
	s_mov_b32 s11, s14
	s_waitcnt lgkmcnt(3)
	v_pk_add_f32 v[158:159], v[130:131], v[24:25]
	v_pk_add_f32 v[24:25], v[130:131], v[24:25] neg_lo:[0,1] neg_hi:[0,1]
	v_pk_add_f32 v[130:131], v[0:1], v[26:27]
	v_pk_add_f32 v[0:1], v[0:1], v[26:27] neg_lo:[0,1] neg_hi:[0,1]
	s_mov_b32 s13, s86
	v_pk_mul_f32 v[26:27], v[0:1], s[16:17]
	s_mov_b32 s4, s21
	v_pk_fma_f32 v[0:1], v[0:1], s[6:7], v[26:27] op_sel:[0,0,1] op_sel_hi:[1,0,0]
	v_pk_add_f32 v[26:27], v[2:3], v[28:29]
	v_pk_add_f32 v[2:3], v[2:3], v[28:29] neg_lo:[0,1] neg_hi:[0,1]
	s_mov_b32 s35, s30
	v_pk_mul_f32 v[28:29], v[2:3], s[18:19]
	s_mov_b32 s8, s19
	v_pk_fma_f32 v[2:3], v[2:3], s[30:31], v[28:29] op_sel:[0,0,1] op_sel_hi:[1,0,0]
	v_pk_add_f32 v[28:29], v[4:5], v[30:31]
	v_pk_add_f32 v[4:5], v[4:5], v[30:31] neg_lo:[0,1] neg_hi:[0,1]
	s_mov_b32 s77, s6
	v_pk_mul_f32 v[30:31], v[4:5], s[20:21]
	s_mov_b32 s28, s17
	v_pk_fma_f32 v[4:5], v[4:5], s[86:87], v[30:31] op_sel:[0,0,1] op_sel_hi:[1,0,0]
	v_pk_add_f32 v[30:31], v[6:7], v[102:103]
	v_pk_add_f32 v[6:7], v[6:7], v[102:103] neg_lo:[0,1] neg_hi:[0,1]
	v_add_u32_e32 v47, 0x10780, v37
	v_pk_mul_f32 v[102:103], v[6:7], s[10:11]
	ds_read_b64 v[138:139], v37 offset:28288
	ds_read_b64 v[140:141], v37 offset:30464
	ds_read_b64 v[142:143], v37 offset:32640
	ds_read_b64 v[144:145], v47
	v_pk_fma_f32 v[6:7], v[6:7], s[14:15], v[102:103] op_sel:[0,0,1] op_sel_hi:[1,0,0]
	v_pk_add_f32 v[102:103], v[8:9], v[110:111]
	v_pk_add_f32 v[8:9], v[8:9], v[110:111] neg_lo:[0,1] neg_hi:[0,1]
	s_nop 0
	v_pk_mul_f32 v[110:111], v[8:9], s[12:13]
	s_nop 0
	v_pk_fma_f32 v[8:9], v[8:9], s[4:5], v[110:111] op_sel:[0,0,1] op_sel_hi:[1,0,0]
	v_pk_add_f32 v[110:111], v[10:11], v[118:119]
	v_pk_add_f32 v[10:11], v[10:11], v[118:119] neg_lo:[0,1] neg_hi:[0,1]
	s_nop 0
	v_pk_mul_f32 v[118:119], v[10:11], s[34:35]
	s_nop 0
	v_pk_fma_f32 v[10:11], v[10:11], s[8:9], v[118:119] op_sel:[0,0,1] op_sel_hi:[1,0,0]
	v_pk_add_f32 v[118:119], v[12:13], v[120:121]
	v_pk_add_f32 v[12:13], v[12:13], v[120:121] neg_lo:[0,1] neg_hi:[0,1]
	s_nop 0
	v_pk_mul_f32 v[120:121], v[12:13], s[76:77]
	s_nop 0
	v_pk_fma_f32 v[12:13], v[12:13], s[28:29], v[120:121] op_sel:[0,0,1] op_sel_hi:[1,0,0]
	v_pk_add_f32 v[120:121], v[14:15], v[122:123]
	v_pk_add_f32 v[14:15], v[14:15], v[122:123] neg_lo:[0,1] neg_hi:[0,1]
	v_pk_add_f32 v[122:123], v[16:17], v[124:125]
	v_pk_add_f32 v[16:17], v[16:17], v[124:125] neg_lo:[0,1] neg_hi:[0,1]
	s_nop 0
	v_pk_mul_f32 v[124:125], v[16:17], s[76:77]
	s_nop 0
	v_pk_fma_f32 v[16:17], v[16:17], s[28:29], v[124:125] op_sel:[0,0,1] op_sel_hi:[1,0,0] neg_lo:[1,0,0] neg_hi:[1,0,0]
	v_pk_add_f32 v[124:125], v[18:19], v[126:127]
	v_pk_add_f32 v[18:19], v[18:19], v[126:127] neg_lo:[0,1] neg_hi:[0,1]
	s_nop 0
	v_pk_mul_f32 v[126:127], v[18:19], s[34:35]
	s_nop 0
	v_pk_fma_f32 v[18:19], v[18:19], s[8:9], v[126:127] op_sel:[0,0,1] op_sel_hi:[1,0,0] neg_lo:[1,0,0] neg_hi:[1,0,0]
	v_pk_add_f32 v[126:127], v[20:21], v[128:129]
	v_pk_add_f32 v[20:21], v[20:21], v[128:129] neg_lo:[0,1] neg_hi:[0,1]
	s_nop 0
	v_pk_mul_f32 v[128:129], v[20:21], s[12:13]
	s_nop 0
	v_pk_fma_f32 v[20:21], v[20:21], s[4:5], v[128:129] op_sel:[0,0,1] op_sel_hi:[1,0,0] neg_lo:[1,0,0] neg_hi:[1,0,0]
	s_waitcnt lgkmcnt(6)
	v_pk_add_f32 v[128:129], v[22:23], v[132:133]
	v_pk_add_f32 v[22:23], v[22:23], v[132:133] neg_lo:[0,1] neg_hi:[0,1]
	s_nop 0
	v_pk_mul_f32 v[132:133], v[22:23], s[10:11]
	s_nop 0
	v_pk_fma_f32 v[22:23], v[22:23], s[14:15], v[132:133] op_sel:[0,0,1] op_sel_hi:[1,0,0] neg_lo:[1,0,0] neg_hi:[1,0,0]
	s_waitcnt lgkmcnt(3)
	v_pk_add_f32 v[132:133], v[138:139], v[134:135]
	v_pk_add_f32 v[134:135], v[138:139], v[134:135] neg_lo:[0,1] neg_hi:[0,1]
	s_nop 0
	v_pk_mul_f32 v[138:139], v[134:135], s[20:21]
	s_nop 0
	v_pk_fma_f32 v[134:135], v[134:135], s[86:87], v[138:139] op_sel:[0,0,1] op_sel_hi:[1,0,0] neg_lo:[1,0,0] neg_hi:[1,0,0]
	s_waitcnt lgkmcnt(2)
	v_pk_add_f32 v[138:139], v[140:141], v[136:137]
	v_pk_add_f32 v[136:137], v[140:141], v[136:137] neg_lo:[0,1] neg_hi:[0,1]
	s_nop 0
	v_pk_mul_f32 v[140:141], v[136:137], s[18:19]
	s_nop 0
	v_pk_fma_f32 v[136:137], v[136:137], s[30:31], v[140:141] op_sel:[0,0,1] op_sel_hi:[1,0,0] neg_lo:[1,0,0] neg_hi:[1,0,0]
	s_waitcnt lgkmcnt(0)
	v_pk_add_f32 v[140:141], v[142:143], v[144:145]
	v_pk_add_f32 v[142:143], v[142:143], v[144:145] neg_lo:[0,1] neg_hi:[0,1]
	s_nop 0
	v_pk_mul_f32 v[144:145], v[142:143], s[16:17]
	s_nop 0
	v_pk_fma_f32 v[142:143], v[142:143], s[6:7], v[144:145] op_sel:[0,0,1] op_sel_hi:[1,0,0] neg_lo:[1,0,0] neg_hi:[1,0,0]
	v_pk_add_f32 v[144:145], v[158:159], v[120:121]
	v_pk_add_f32 v[120:121], v[158:159], v[120:121] neg_lo:[0,1] neg_hi:[0,1]
	v_pk_add_f32 v[158:159], v[130:131], v[122:123]
	v_pk_add_f32 v[122:123], v[130:131], v[122:123] neg_lo:[0,1] neg_hi:[0,1]
	s_nop 0
	v_pk_mul_f32 v[130:131], v[122:123], s[18:19]
	s_nop 0
	v_pk_fma_f32 v[122:123], v[122:123], s[30:31], v[130:131] op_sel:[0,0,1] op_sel_hi:[1,0,0]
	v_pk_add_f32 v[130:131], v[26:27], v[124:125]
	v_pk_add_f32 v[26:27], v[26:27], v[124:125] neg_lo:[0,1] neg_hi:[0,1]
	s_nop 0
	v_pk_mul_f32 v[124:125], v[26:27], s[10:11]
	s_nop 0
	v_pk_fma_f32 v[26:27], v[26:27], s[14:15], v[124:125] op_sel:[0,0,1] op_sel_hi:[1,0,0]
	v_pk_add_f32 v[124:125], v[28:29], v[126:127]
	v_pk_add_f32 v[28:29], v[28:29], v[126:127] neg_lo:[0,1] neg_hi:[0,1]
	s_nop 0
	v_pk_mul_f32 v[126:127], v[28:29], s[34:35]
	s_nop 0
	v_pk_fma_f32 v[28:29], v[28:29], s[8:9], v[126:127] op_sel:[0,0,1] op_sel_hi:[1,0,0]
	v_pk_add_f32 v[126:127], v[30:31], v[128:129]
	v_pk_add_f32 v[30:31], v[30:31], v[128:129] neg_lo:[0,1] neg_hi:[0,1]
	v_pk_add_f32 v[128:129], v[102:103], v[132:133]
	v_pk_add_f32 v[102:103], v[102:103], v[132:133] neg_lo:[0,1] neg_hi:[0,1]
	s_nop 0
	v_pk_mul_f32 v[132:133], v[102:103], s[34:35]
	s_nop 0
	v_pk_fma_f32 v[102:103], v[102:103], s[8:9], v[132:133] op_sel:[0,0,1] op_sel_hi:[1,0,0] neg_lo:[1,0,0] neg_hi:[1,0,0]
	v_pk_add_f32 v[132:133], v[110:111], v[138:139]
	v_pk_add_f32 v[110:111], v[110:111], v[138:139] neg_lo:[0,1] neg_hi:[0,1]
	s_nop 0
	v_pk_mul_f32 v[138:139], v[110:111], s[10:11]
	s_nop 0
	v_pk_fma_f32 v[110:111], v[110:111], s[14:15], v[138:139] op_sel:[0,0,1] op_sel_hi:[1,0,0] neg_lo:[1,0,0] neg_hi:[1,0,0]
	v_pk_add_f32 v[138:139], v[118:119], v[140:141]
	v_pk_add_f32 v[118:119], v[118:119], v[140:141] neg_lo:[0,1] neg_hi:[0,1]
	s_nop 0
	v_pk_mul_f32 v[140:141], v[118:119], s[18:19]
	s_nop 0
	v_pk_fma_f32 v[118:119], v[118:119], s[30:31], v[140:141] op_sel:[0,0,1] op_sel_hi:[1,0,0] neg_lo:[1,0,0] neg_hi:[1,0,0]
	v_pk_add_f32 v[140:141], v[24:25], v[14:15] op_sel:[0,1] op_sel_hi:[1,0] neg_hi:[0,1]
	v_pk_add_f32 v[14:15], v[24:25], v[14:15] op_sel:[0,1] op_sel_hi:[1,0] neg_lo:[0,1]
	v_pk_add_f32 v[24:25], v[0:1], v[16:17]
	v_pk_add_f32 v[0:1], v[0:1], v[16:17] neg_lo:[0,1] neg_hi:[0,1]
	s_nop 0
	v_pk_mul_f32 v[16:17], v[0:1], s[18:19]
	s_nop 0
	v_pk_fma_f32 v[0:1], v[0:1], s[30:31], v[16:17] op_sel:[0,0,1] op_sel_hi:[1,0,0]
	v_pk_add_f32 v[16:17], v[2:3], v[18:19]
	v_pk_add_f32 v[2:3], v[2:3], v[18:19] neg_lo:[0,1] neg_hi:[0,1]
	s_nop 0
	v_pk_mul_f32 v[18:19], v[2:3], s[10:11]
	s_nop 0
	v_pk_fma_f32 v[2:3], v[2:3], s[14:15], v[18:19] op_sel:[0,0,1] op_sel_hi:[1,0,0]
	v_pk_add_f32 v[18:19], v[4:5], v[20:21]
	v_pk_add_f32 v[4:5], v[4:5], v[20:21] neg_lo:[0,1] neg_hi:[0,1]
	s_nop 0
	v_pk_mul_f32 v[20:21], v[4:5], s[34:35]
	s_nop 0
	v_pk_fma_f32 v[4:5], v[4:5], s[8:9], v[20:21] op_sel:[0,0,1] op_sel_hi:[1,0,0]
	v_pk_add_f32 v[20:21], v[6:7], v[22:23]
	v_pk_add_f32 v[6:7], v[6:7], v[22:23] neg_lo:[0,1] neg_hi:[0,1]
	v_pk_add_f32 v[22:23], v[8:9], v[134:135]
	v_pk_add_f32 v[8:9], v[8:9], v[134:135] neg_lo:[0,1] neg_hi:[0,1]
	s_nop 0
	v_pk_mul_f32 v[134:135], v[8:9], s[34:35]
	s_nop 0
	v_pk_fma_f32 v[8:9], v[8:9], s[8:9], v[134:135] op_sel:[0,0,1] op_sel_hi:[1,0,0] neg_lo:[1,0,0] neg_hi:[1,0,0]
	v_pk_add_f32 v[134:135], v[10:11], v[136:137]
	v_pk_add_f32 v[10:11], v[10:11], v[136:137] neg_lo:[0,1] neg_hi:[0,1]
	s_nop 0
	v_pk_mul_f32 v[136:137], v[10:11], s[10:11]
	s_nop 0
	v_pk_fma_f32 v[10:11], v[10:11], s[14:15], v[136:137] op_sel:[0,0,1] op_sel_hi:[1,0,0] neg_lo:[1,0,0] neg_hi:[1,0,0]
	v_pk_add_f32 v[136:137], v[12:13], v[142:143]
	v_pk_add_f32 v[12:13], v[12:13], v[142:143] neg_lo:[0,1] neg_hi:[0,1]
	s_nop 0
	v_pk_mul_f32 v[142:143], v[12:13], s[18:19]
	s_nop 0
	v_pk_fma_f32 v[12:13], v[12:13], s[30:31], v[142:143] op_sel:[0,0,1] op_sel_hi:[1,0,0] neg_lo:[1,0,0] neg_hi:[1,0,0]
	v_pk_add_f32 v[142:143], v[144:145], v[126:127]
	v_pk_add_f32 v[126:127], v[144:145], v[126:127] neg_lo:[0,1] neg_hi:[0,1]
	v_pk_add_f32 v[144:145], v[158:159], v[128:129]
	v_pk_add_f32 v[128:129], v[158:159], v[128:129] neg_lo:[0,1] neg_hi:[0,1]
	s_nop 0
	v_pk_mul_f32 v[158:159], v[128:129], s[10:11]
	s_nop 0
	v_pk_fma_f32 v[128:129], v[128:129], s[14:15], v[158:159] op_sel:[0,0,1] op_sel_hi:[1,0,0]
	v_pk_add_f32 v[158:159], v[130:131], v[132:133]
	v_pk_add_f32 v[130:131], v[130:131], v[132:133] neg_lo:[0,1] neg_hi:[0,1]
	v_pk_add_f32 v[132:133], v[124:125], v[138:139]
	v_pk_add_f32 v[124:125], v[124:125], v[138:139] neg_lo:[0,1] neg_hi:[0,1]
	s_nop 0
	v_pk_mul_f32 v[138:139], v[124:125], s[10:11]
	s_nop 0
	v_pk_fma_f32 v[124:125], v[124:125], s[14:15], v[138:139] op_sel:[0,0,1] op_sel_hi:[1,0,0] neg_lo:[1,0,0] neg_hi:[1,0,0]
	v_pk_add_f32 v[138:139], v[120:121], v[30:31] op_sel:[0,1] op_sel_hi:[1,0] neg_hi:[0,1]
	v_pk_add_f32 v[30:31], v[120:121], v[30:31] op_sel:[0,1] op_sel_hi:[1,0] neg_lo:[0,1]
	v_pk_add_f32 v[120:121], v[122:123], v[102:103]
	v_pk_add_f32 v[102:103], v[122:123], v[102:103] neg_lo:[0,1] neg_hi:[0,1]
	v_pk_add_f32 v[160:161], v[128:129], v[124:125]
	v_pk_mul_f32 v[122:123], v[102:103], s[10:11]
	v_pk_add_f32 v[124:125], v[128:129], v[124:125] neg_lo:[0,1] neg_hi:[0,1]
	v_pk_fma_f32 v[102:103], v[102:103], s[14:15], v[122:123] op_sel:[0,0,1] op_sel_hi:[1,0,0]
	v_pk_add_f32 v[122:123], v[26:27], v[110:111]
	v_pk_add_f32 v[26:27], v[26:27], v[110:111] neg_lo:[0,1] neg_hi:[0,1]
	v_pk_add_f32 v[110:111], v[28:29], v[118:119]
	v_pk_add_f32 v[28:29], v[28:29], v[118:119] neg_lo:[0,1] neg_hi:[0,1]
	s_nop 0
	v_pk_mul_f32 v[118:119], v[28:29], s[10:11]
	v_pk_add_f32 v[166:167], v[120:121], v[110:111]
	v_pk_fma_f32 v[28:29], v[28:29], s[14:15], v[118:119] op_sel:[0,0,1] op_sel_hi:[1,0,0] neg_lo:[1,0,0] neg_hi:[1,0,0]
	v_pk_add_f32 v[118:119], v[140:141], v[20:21]
	v_pk_add_f32 v[20:21], v[140:141], v[20:21] neg_lo:[0,1] neg_hi:[0,1]
	v_pk_add_f32 v[140:141], v[24:25], v[22:23]
	v_pk_add_f32 v[22:23], v[24:25], v[22:23] neg_lo:[0,1] neg_hi:[0,1]
	v_pk_add_f32 v[110:111], v[120:121], v[110:111] neg_lo:[0,1] neg_hi:[0,1]
	v_pk_mul_f32 v[24:25], v[22:23], s[10:11]
	v_pk_add_f32 v[168:169], v[30:31], v[26:27] op_sel:[0,1] op_sel_hi:[1,0] neg_hi:[0,1]
	v_pk_fma_f32 v[22:23], v[22:23], s[14:15], v[24:25] op_sel:[0,0,1] op_sel_hi:[1,0,0]
	v_pk_add_f32 v[24:25], v[16:17], v[134:135]
	v_pk_add_f32 v[16:17], v[16:17], v[134:135] neg_lo:[0,1] neg_hi:[0,1]
	v_pk_add_f32 v[134:135], v[18:19], v[136:137]
	v_pk_add_f32 v[18:19], v[18:19], v[136:137] neg_lo:[0,1] neg_hi:[0,1]
	s_nop 0
	v_pk_mul_f32 v[136:137], v[18:19], s[10:11]
	v_pk_add_f32 v[26:27], v[30:31], v[26:27] op_sel:[0,1] op_sel_hi:[1,0] neg_lo:[0,1]
	v_pk_fma_f32 v[18:19], v[18:19], s[14:15], v[136:137] op_sel:[0,0,1] op_sel_hi:[1,0,0] neg_lo:[1,0,0] neg_hi:[1,0,0]
	v_pk_add_f32 v[136:137], v[14:15], v[6:7] op_sel:[0,1] op_sel_hi:[1,0] neg_hi:[0,1]
	v_pk_add_f32 v[6:7], v[14:15], v[6:7] op_sel:[0,1] op_sel_hi:[1,0] neg_lo:[0,1]
	v_pk_add_f32 v[14:15], v[0:1], v[8:9]
	v_pk_add_f32 v[0:1], v[0:1], v[8:9] neg_lo:[0,1] neg_hi:[0,1]
	v_pk_add_f32 v[30:31], v[102:103], v[28:29]
	v_pk_mul_f32 v[8:9], v[0:1], s[10:11]
	v_pk_add_f32 v[28:29], v[102:103], v[28:29] neg_lo:[0,1] neg_hi:[0,1]
	v_pk_fma_f32 v[0:1], v[0:1], s[14:15], v[8:9] op_sel:[0,0,1] op_sel_hi:[1,0,0]
	v_pk_add_f32 v[8:9], v[2:3], v[10:11]
	v_pk_add_f32 v[2:3], v[2:3], v[10:11] neg_lo:[0,1] neg_hi:[0,1]
	v_pk_add_f32 v[10:11], v[4:5], v[12:13]
	v_pk_add_f32 v[4:5], v[4:5], v[12:13] neg_lo:[0,1] neg_hi:[0,1]
	s_nop 0
	v_pk_mul_f32 v[12:13], v[4:5], s[10:11]
	v_pk_add_f32 v[170:171], v[118:119], v[24:25]
	v_pk_fma_f32 v[4:5], v[4:5], s[14:15], v[12:13] op_sel:[0,0,1] op_sel_hi:[1,0,0] neg_lo:[1,0,0] neg_hi:[1,0,0]
	v_pk_add_f32 v[12:13], v[142:143], v[158:159]
	v_pk_add_f32 v[142:143], v[142:143], v[158:159] neg_lo:[0,1] neg_hi:[0,1]
	v_pk_add_f32 v[158:159], v[144:145], v[132:133]
	v_pk_add_f32 v[132:133], v[144:145], v[132:133] neg_lo:[0,1] neg_hi:[0,1]
	v_pk_add_f32 v[182:183], v[118:119], v[24:25] neg_lo:[0,1] neg_hi:[0,1]
	v_pk_add_f32 v[184:185], v[140:141], v[134:135]
	v_pk_add_f32 v[24:25], v[140:141], v[134:135] neg_lo:[0,1] neg_hi:[0,1]
	v_pk_add_f32 v[140:141], v[20:21], v[16:17] op_sel:[0,1] op_sel_hi:[1,0] neg_hi:[0,1]
	v_pk_add_f32 v[186:187], v[20:21], v[16:17] op_sel:[0,1] op_sel_hi:[1,0] neg_lo:[0,1]
	v_pk_add_f32 v[16:17], v[22:23], v[18:19] neg_lo:[0,1] neg_hi:[0,1]
	v_pk_add_f32 v[192:193], v[136:137], v[8:9]
	v_pk_add_f32 v[194:195], v[136:137], v[8:9] neg_lo:[0,1] neg_hi:[0,1]
	v_pk_add_f32 v[8:9], v[14:15], v[10:11] neg_lo:[0,1] neg_hi:[0,1]
	v_pk_add_f32 v[198:199], v[6:7], v[2:3] op_sel:[0,1] op_sel_hi:[1,0] neg_hi:[0,1]
	v_pk_add_f32 v[200:201], v[6:7], v[2:3] op_sel:[0,1] op_sel_hi:[1,0] neg_lo:[0,1]
	v_pk_add_f32 v[2:3], v[0:1], v[4:5]
	v_pk_add_f32 v[0:1], v[0:1], v[4:5] neg_lo:[0,1] neg_hi:[0,1]
	v_pk_add_f32 v[144:145], v[126:127], v[130:131] op_sel:[0,1] op_sel_hi:[1,0] neg_hi:[0,1]
	v_pk_add_f32 v[130:131], v[126:127], v[130:131] op_sel:[0,1] op_sel_hi:[1,0] neg_lo:[0,1]
	v_pk_mul_f32 v[162:163], v[124:125], s[22:23]
	v_pk_add_f32 v[164:165], v[138:139], v[122:123]
	v_pk_add_f32 v[138:139], v[138:139], v[122:123] neg_lo:[0,1] neg_hi:[0,1]
	v_pk_mul_f32 v[102:103], v[28:29], s[22:23]
	v_pk_mul_f32 v[134:135], v[24:25], s[22:23]
	v_pk_add_f32 v[188:189], v[22:23], v[18:19]
	v_pk_mul_f32 v[190:191], v[16:17], s[22:23]
	v_pk_add_f32 v[136:137], v[14:15], v[10:11]
	v_pk_mul_f32 v[196:197], v[8:9], s[22:23]
	v_pk_mul_f32 v[202:203], v[0:1], s[22:23]
	v_pk_add_f32 v[28:29], v[12:13], v[158:159]
	v_pk_add_f32 v[128:129], v[12:13], v[158:159] neg_lo:[0,1] neg_hi:[0,1]
	v_pk_add_f32 v[24:25], v[142:143], v[132:133] op_sel:[0,1] op_sel_hi:[1,0] neg_hi:[0,1]
	v_pk_add_f32 v[126:127], v[142:143], v[132:133] op_sel:[0,1] op_sel_hi:[1,0] neg_lo:[0,1]
	v_pk_add_f32 v[20:21], v[144:145], v[160:161]
	v_pk_add_f32 v[124:125], v[144:145], v[160:161] neg_lo:[0,1] neg_hi:[0,1]
	v_pk_add_f32 v[16:17], v[130:131], v[162:163] op_sel:[0,1] op_sel_hi:[1,0]
	v_pk_add_f32 v[122:123], v[130:131], v[162:163] op_sel:[0,1] op_sel_hi:[1,0] neg_lo:[0,1] neg_hi:[0,1]
	v_pk_add_f32 v[12:13], v[164:165], v[166:167]
	v_pk_add_f32 v[120:121], v[164:165], v[166:167] neg_lo:[0,1] neg_hi:[0,1]
	v_pk_add_f32 v[8:9], v[138:139], v[110:111] op_sel:[0,1] op_sel_hi:[1,0] neg_hi:[0,1]
	v_pk_add_f32 v[118:119], v[138:139], v[110:111] op_sel:[0,1] op_sel_hi:[1,0] neg_lo:[0,1]
	v_pk_add_f32 v[4:5], v[168:169], v[30:31]
	v_pk_add_f32 v[110:111], v[168:169], v[30:31] neg_lo:[0,1] neg_hi:[0,1]
	v_pk_add_f32 v[0:1], v[26:27], v[102:103] op_sel:[0,1] op_sel_hi:[1,0]
	v_pk_add_f32 v[102:103], v[26:27], v[102:103] op_sel:[0,1] op_sel_hi:[1,0] neg_lo:[0,1] neg_hi:[0,1]
	v_pk_add_f32 v[30:31], v[170:171], v[184:185]
	v_pk_add_f32 v[144:145], v[170:171], v[184:185] neg_lo:[0,1] neg_hi:[0,1]
	v_pk_add_f32 v[26:27], v[182:183], v[134:135] op_sel:[0,1] op_sel_hi:[1,0]
	v_pk_add_f32 v[142:143], v[182:183], v[134:135] op_sel:[0,1] op_sel_hi:[1,0] neg_lo:[0,1] neg_hi:[0,1]
	v_pk_add_f32 v[22:23], v[140:141], v[188:189]
	v_pk_add_f32 v[140:141], v[140:141], v[188:189] neg_lo:[0,1] neg_hi:[0,1]
	v_pk_add_f32 v[18:19], v[186:187], v[190:191] op_sel:[0,1] op_sel_hi:[1,0]
	v_pk_add_f32 v[138:139], v[186:187], v[190:191] op_sel:[0,1] op_sel_hi:[1,0] neg_lo:[0,1] neg_hi:[0,1]
	v_pk_add_f32 v[14:15], v[192:193], v[136:137]
	v_pk_add_f32 v[136:137], v[192:193], v[136:137] neg_lo:[0,1] neg_hi:[0,1]
	v_pk_add_f32 v[10:11], v[194:195], v[196:197] op_sel:[0,1] op_sel_hi:[1,0]
	v_pk_add_f32 v[134:135], v[194:195], v[196:197] op_sel:[0,1] op_sel_hi:[1,0] neg_lo:[0,1] neg_hi:[0,1]
	v_pk_add_f32 v[6:7], v[198:199], v[2:3]
	v_pk_add_f32 v[132:133], v[198:199], v[2:3] neg_lo:[0,1] neg_hi:[0,1]
	v_pk_add_f32 v[2:3], v[200:201], v[202:203] op_sel:[0,1] op_sel_hi:[1,0]
	v_pk_add_f32 v[130:131], v[200:201], v[202:203] op_sel:[0,1] op_sel_hi:[1,0] neg_lo:[0,1] neg_hi:[0,1]

.LBB0_485:
	v_add_u32_e32 v160, 0x11000, v155
	v_lshlrev_b32_e32 v161, 3, v154
	v_add_u32_e32 v161, 0x2200, v161
	v_add_u32_e32 v162, 0x11100, v156
	v_cmp_ne_u32_e32 vcc, 0, v32
	v_cndmask_b32_e32 v163, 0, v154, vcc
	v_lshlrev_b32_e32 v163, 3, v163
	v_add_u32_e32 v163, 0x11000, v163
	ds_read_b64 v[214:215], v160 offset:0
	ds_read_b64 v[216:217], v163
	ds_read_b64 v[218:219], v155 offset:0
	ds_read_b64 v[220:221], v160 offset:4352
	ds_read_b64 v[222:223], v162 offset:60928
	ds_read_b64 v[224:225], v155 offset:4352
	ds_read_b64 v[226:227], v160 offset:8704
	ds_read_b64 v[228:229], v161 offset:52224
	ds_read_b64 v[230:231], v155 offset:8704
	ds_read_b64 v[232:233], v160 offset:13056
	ds_read_b64 v[234:235], v162 offset:52224
	ds_read_b64 v[236:237], v155 offset:13056
	s_waitcnt lgkmcnt(9)
	v_add_f32_e32 v164, v215, v217
	v_sub_f32_e32 v165, v214, v216
	v_mul_f32_e32 v216, 0.5, v164
	v_mul_f32_e32 v214, -0.5, v165
	v_pk_mul_f32 v[214:215], v[218:219], v[214:215] op_sel:[1,0] op_sel_hi:[0,0]
	v_pk_fma_f32 v[158:159], v[218:219], v[216:217], v[214:215] neg_lo:[0,0,1] neg_hi:[0,0,1]
	v_pk_fma_f32 v[216:217], v[218:219], v[216:217], v[214:215] op_sel_hi:[1,0,1]
	s_nop 0
	v_mov_b32_e32 v159, v217
	v_pk_mul_f32 v[218:219], v[158:159], s[24:25]
	ds_write_b64 v155, v[218:219] offset:0
	s_waitcnt lgkmcnt(7)
	v_add_f32_e32 v164, v221, v223
	v_sub_f32_e32 v165, v220, v222
	v_mul_f32_e32 v222, 0.5, v164
	v_mul_f32_e32 v220, -0.5, v165
	v_pk_mul_f32 v[220:221], v[224:225], v[220:221] op_sel:[1,0] op_sel_hi:[0,0]
	v_pk_fma_f32 v[158:159], v[224:225], v[222:223], v[220:221] neg_lo:[0,0,1] neg_hi:[0,0,1]
	v_pk_fma_f32 v[222:223], v[224:225], v[222:223], v[220:221] op_sel_hi:[1,0,1]
	s_nop 0
	v_mov_b32_e32 v159, v223
	v_pk_mul_f32 v[224:225], v[158:159], s[24:25]
	ds_write_b64 v155, v[224:225] offset:4352
	s_waitcnt lgkmcnt(5)
	v_add_f32_e32 v164, v227, v229
	v_sub_f32_e32 v165, v226, v228
	v_mul_f32_e32 v228, 0.5, v164
	v_mul_f32_e32 v226, -0.5, v165
	v_pk_mul_f32 v[226:227], v[230:231], v[226:227] op_sel:[1,0] op_sel_hi:[0,0]
	v_pk_fma_f32 v[158:159], v[230:231], v[228:229], v[226:227] neg_lo:[0,0,1] neg_hi:[0,0,1]
	v_pk_fma_f32 v[228:229], v[230:231], v[228:229], v[226:227] op_sel_hi:[1,0,1]
	s_nop 0
	v_mov_b32_e32 v159, v229
	v_pk_mul_f32 v[230:231], v[158:159], s[24:25]
	ds_write_b64 v155, v[230:231] offset:8704
	s_waitcnt lgkmcnt(3)
	v_add_f32_e32 v164, v233, v235
	v_sub_f32_e32 v165, v232, v234
	v_mul_f32_e32 v234, 0.5, v164
	v_mul_f32_e32 v232, -0.5, v165
	v_pk_mul_f32 v[232:233], v[236:237], v[232:233] op_sel:[1,0] op_sel_hi:[0,0]
	v_pk_fma_f32 v[158:159], v[236:237], v[234:235], v[232:233] neg_lo:[0,0,1] neg_hi:[0,0,1]
	v_pk_fma_f32 v[234:235], v[236:237], v[234:235], v[232:233] op_sel_hi:[1,0,1]
	s_nop 0
	v_mov_b32_e32 v159, v235
	v_pk_mul_f32 v[236:237], v[158:159], s[24:25]
	ds_write_b64 v155, v[236:237] offset:13056
	ds_read_b64 v[182:183], v160 offset:17408
	ds_read_b64 v[184:185], v161 offset:43520
	ds_read_b64 v[186:187], v155 offset:17408
	ds_read_b64 v[188:189], v160 offset:21760
	ds_read_b64 v[190:191], v162 offset:43520
	ds_read_b64 v[192:193], v155 offset:21760
	ds_read_b64 v[194:195], v160 offset:26112
	ds_read_b64 v[196:197], v161 offset:34816
	ds_read_b64 v[198:199], v155 offset:26112
	ds_read_b64 v[200:201], v160 offset:30464
	ds_read_b64 v[202:203], v162 offset:34816
	ds_read_b64 v[238:239], v155 offset:30464
	s_waitcnt lgkmcnt(9)
	v_add_f32_e32 v164, v183, v185
	v_sub_f32_e32 v165, v182, v184
	v_mul_f32_e32 v184, 0.5, v164
	v_mul_f32_e32 v182, -0.5, v165
	v_pk_mul_f32 v[182:183], v[186:187], v[182:183] op_sel:[1,0] op_sel_hi:[0,0]
	v_pk_fma_f32 v[158:159], v[186:187], v[184:185], v[182:183] neg_lo:[0,0,1] neg_hi:[0,0,1]
	v_pk_fma_f32 v[184:185], v[186:187], v[184:185], v[182:183] op_sel_hi:[1,0,1]
	s_nop 0
	v_mov_b32_e32 v159, v185
	v_pk_mul_f32 v[186:187], v[158:159], s[24:25]
	ds_write_b64 v155, v[186:187] offset:17408
	s_waitcnt lgkmcnt(7)
	v_add_f32_e32 v164, v189, v191
	v_sub_f32_e32 v165, v188, v190
	v_mul_f32_e32 v190, 0.5, v164
	v_mul_f32_e32 v188, -0.5, v165
	v_pk_mul_f32 v[188:189], v[192:193], v[188:189] op_sel:[1,0] op_sel_hi:[0,0]
	v_pk_fma_f32 v[158:159], v[192:193], v[190:191], v[188:189] neg_lo:[0,0,1] neg_hi:[0,0,1]
	v_pk_fma_f32 v[190:191], v[192:193], v[190:191], v[188:189] op_sel_hi:[1,0,1]
	s_nop 0
	v_mov_b32_e32 v159, v191
	v_pk_mul_f32 v[192:193], v[158:159], s[24:25]
	ds_write_b64 v155, v[192:193] offset:21760
	s_waitcnt lgkmcnt(5)
	v_add_f32_e32 v164, v195, v197
	v_sub_f32_e32 v165, v194, v196
	v_mul_f32_e32 v196, 0.5, v164
	v_mul_f32_e32 v194, -0.5, v165
	v_pk_mul_f32 v[194:195], v[198:199], v[194:195] op_sel:[1,0] op_sel_hi:[0,0]
	v_pk_fma_f32 v[158:159], v[198:199], v[196:197], v[194:195] neg_lo:[0,0,1] neg_hi:[0,0,1]
	v_pk_fma_f32 v[196:197], v[198:199], v[196:197], v[194:195] op_sel_hi:[1,0,1]
	s_nop 0
	v_mov_b32_e32 v159, v197
	v_pk_mul_f32 v[198:199], v[158:159], s[24:25]
	ds_write_b64 v155, v[198:199] offset:26112
	s_waitcnt lgkmcnt(3)
	v_add_f32_e32 v164, v201, v203
	v_sub_f32_e32 v165, v200, v202
	v_mul_f32_e32 v202, 0.5, v164
	v_mul_f32_e32 v200, -0.5, v165
	v_pk_mul_f32 v[200:201], v[238:239], v[200:201] op_sel:[1,0] op_sel_hi:[0,0]
	v_pk_fma_f32 v[158:159], v[238:239], v[202:203], v[200:201] neg_lo:[0,0,1] neg_hi:[0,0,1]
	v_pk_fma_f32 v[202:203], v[238:239], v[202:203], v[200:201] op_sel_hi:[1,0,1]
	s_nop 0
	v_mov_b32_e32 v159, v203
	v_pk_mul_f32 v[238:239], v[158:159], s[24:25]
	ds_write_b64 v155, v[238:239] offset:30464
	ds_read_b64 v[214:215], v160 offset:34816
	ds_read_b64 v[216:217], v161 offset:26112
	ds_read_b64 v[218:219], v155 offset:34816
	ds_read_b64 v[220:221], v160 offset:39168
	ds_read_b64 v[222:223], v162 offset:26112
	ds_read_b64 v[224:225], v155 offset:39168
	ds_read_b64 v[226:227], v160 offset:43520
	ds_read_b64 v[228:229], v161 offset:17408
	ds_read_b64 v[230:231], v155 offset:43520
	ds_read_b64 v[232:233], v160 offset:47872
	ds_read_b64 v[234:235], v162 offset:17408
	ds_read_b64 v[236:237], v155 offset:47872
	s_waitcnt lgkmcnt(9)
	v_add_f32_e32 v164, v215, v217
	v_sub_f32_e32 v165, v214, v216
	v_mul_f32_e32 v216, 0.5, v164
	v_mul_f32_e32 v214, -0.5, v165
	v_pk_mul_f32 v[214:215], v[218:219], v[214:215] op_sel:[1,0] op_sel_hi:[0,0]
	v_pk_fma_f32 v[158:159], v[218:219], v[216:217], v[214:215] neg_lo:[0,0,1] neg_hi:[0,0,1]
	v_pk_fma_f32 v[216:217], v[218:219], v[216:217], v[214:215] op_sel_hi:[1,0,1]
	s_nop 0
	v_mov_b32_e32 v159, v217
	v_pk_mul_f32 v[218:219], v[158:159], s[24:25]
	ds_write_b64 v155, v[218:219] offset:34816
	s_waitcnt lgkmcnt(7)
	v_add_f32_e32 v164, v221, v223
	v_sub_f32_e32 v165, v220, v222
	v_mul_f32_e32 v222, 0.5, v164
	v_mul_f32_e32 v220, -0.5, v165
	v_pk_mul_f32 v[220:221], v[224:225], v[220:221] op_sel:[1,0] op_sel_hi:[0,0]
	v_pk_fma_f32 v[158:159], v[224:225], v[222:223], v[220:221] neg_lo:[0,0,1] neg_hi:[0,0,1]
	v_pk_fma_f32 v[222:223], v[224:225], v[222:223], v[220:221] op_sel_hi:[1,0,1]
	s_nop 0
	v_mov_b32_e32 v159, v223
	v_pk_mul_f32 v[224:225], v[158:159], s[24:25]
	ds_write_b64 v155, v[224:225] offset:39168
	s_waitcnt lgkmcnt(5)
	v_add_f32_e32 v164, v227, v229
	v_sub_f32_e32 v165, v226, v228
	v_mul_f32_e32 v228, 0.5, v164
	v_mul_f32_e32 v226, -0.5, v165
	v_pk_mul_f32 v[226:227], v[230:231], v[226:227] op_sel:[1,0] op_sel_hi:[0,0]
	v_pk_fma_f32 v[158:159], v[230:231], v[228:229], v[226:227] neg_lo:[0,0,1] neg_hi:[0,0,1]
	v_pk_fma_f32 v[228:229], v[230:231], v[228:229], v[226:227] op_sel_hi:[1,0,1]
	s_nop 0
	v_mov_b32_e32 v159, v229
	v_pk_mul_f32 v[230:231], v[158:159], s[24:25]
	ds_write_b64 v155, v[230:231] offset:43520
	s_waitcnt lgkmcnt(3)
	v_add_f32_e32 v164, v233, v235
	v_sub_f32_e32 v165, v232, v234
	v_mul_f32_e32 v234, 0.5, v164
	v_mul_f32_e32 v232, -0.5, v165
	v_pk_mul_f32 v[232:233], v[236:237], v[232:233] op_sel:[1,0] op_sel_hi:[0,0]
	v_pk_fma_f32 v[158:159], v[236:237], v[234:235], v[232:233] neg_lo:[0,0,1] neg_hi:[0,0,1]
	v_pk_fma_f32 v[234:235], v[236:237], v[234:235], v[232:233] op_sel_hi:[1,0,1]
	s_nop 0
	v_mov_b32_e32 v159, v235
	v_pk_mul_f32 v[236:237], v[158:159], s[24:25]
	ds_write_b64 v155, v[236:237] offset:47872
	ds_read_b64 v[182:183], v160 offset:52224
	ds_read_b64 v[184:185], v161 offset:8704
	ds_read_b64 v[186:187], v155 offset:52224
	ds_read_b64 v[188:189], v160 offset:56576
	ds_read_b64 v[190:191], v162 offset:8704
	ds_read_b64 v[192:193], v155 offset:56576
	ds_read_b64 v[194:195], v160 offset:60928
	ds_read_b64 v[196:197], v161 offset:0
	ds_read_b64 v[198:199], v155 offset:60928
	ds_read_b64 v[200:201], v160 offset:65280
	ds_read_b64 v[202:203], v162 offset:0
	ds_read_b64 v[238:239], v155 offset:65280
	s_waitcnt lgkmcnt(9)
	v_add_f32_e32 v164, v183, v185
	v_sub_f32_e32 v165, v182, v184
	v_mul_f32_e32 v184, 0.5, v164
	v_mul_f32_e32 v182, -0.5, v165
	v_pk_mul_f32 v[182:183], v[186:187], v[182:183] op_sel:[1,0] op_sel_hi:[0,0]
	v_pk_fma_f32 v[158:159], v[186:187], v[184:185], v[182:183] neg_lo:[0,0,1] neg_hi:[0,0,1]
	v_pk_fma_f32 v[184:185], v[186:187], v[184:185], v[182:183] op_sel_hi:[1,0,1]
	s_nop 0
	v_mov_b32_e32 v159, v185
	v_pk_mul_f32 v[186:187], v[158:159], s[24:25]
	ds_write_b64 v155, v[186:187] offset:52224
	s_waitcnt lgkmcnt(7)
	v_add_f32_e32 v164, v189, v191
	v_sub_f32_e32 v165, v188, v190
	v_mul_f32_e32 v190, 0.5, v164
	v_mul_f32_e32 v188, -0.5, v165
	v_pk_mul_f32 v[188:189], v[192:193], v[188:189] op_sel:[1,0] op_sel_hi:[0,0]
	v_pk_fma_f32 v[158:159], v[192:193], v[190:191], v[188:189] neg_lo:[0,0,1] neg_hi:[0,0,1]
	v_pk_fma_f32 v[190:191], v[192:193], v[190:191], v[188:189] op_sel_hi:[1,0,1]
	s_nop 0
	v_mov_b32_e32 v159, v191
	v_pk_mul_f32 v[192:193], v[158:159], s[24:25]
	ds_write_b64 v155, v[192:193] offset:56576
	s_waitcnt lgkmcnt(5)
	v_add_f32_e32 v164, v195, v197
	v_sub_f32_e32 v165, v194, v196
	v_mul_f32_e32 v196, 0.5, v164
	v_mul_f32_e32 v194, -0.5, v165
	v_pk_mul_f32 v[194:195], v[198:199], v[194:195] op_sel:[1,0] op_sel_hi:[0,0]
	v_pk_fma_f32 v[158:159], v[198:199], v[196:197], v[194:195] neg_lo:[0,0,1] neg_hi:[0,0,1]
	v_pk_fma_f32 v[196:197], v[198:199], v[196:197], v[194:195] op_sel_hi:[1,0,1]
	s_nop 0
	v_mov_b32_e32 v159, v197
	v_pk_mul_f32 v[198:199], v[158:159], s[24:25]
	ds_write_b64 v155, v[198:199] offset:60928
	s_waitcnt lgkmcnt(3)
	v_add_f32_e32 v164, v201, v203
	v_sub_f32_e32 v165, v200, v202
	v_mul_f32_e32 v202, 0.5, v164
	v_mul_f32_e32 v200, -0.5, v165
	v_pk_mul_f32 v[200:201], v[238:239], v[200:201] op_sel:[1,0] op_sel_hi:[0,0]
	v_pk_fma_f32 v[158:159], v[238:239], v[202:203], v[200:201] neg_lo:[0,0,1] neg_hi:[0,0,1]
	v_pk_fma_f32 v[202:203], v[238:239], v[202:203], v[200:201] op_sel_hi:[1,0,1]
	s_nop 0
	v_mov_b32_e32 v159, v203
	v_pk_mul_f32 v[238:239], v[158:159], s[24:25]
	ds_write_b64 v155, v[238:239] offset:65280
	s_mov_b32 s0, 16
	s_cmp_lg_u32 s0, 16
	s_waitcnt lgkmcnt(0)
	s_barrier
	s_and_saveexec_b64 s[0:1], s[40:41]
	s_cbranch_execz .LBB0_488
	ds_read_b64 v[0:1], v37 offset:2176
	ds_read_b64 v[2:3], v37 offset:4352
	ds_read_b64 v[4:5], v37 offset:6528
	ds_read_b64 v[6:7], v37 offset:8704
	ds_read_b64 v[8:9], v37 offset:10880
	ds_read_b64 v[10:11], v37 offset:13056
	ds_read_b64 v[12:13], v37 offset:15232
	ds_read_b64 v[14:15], v37 offset:17408
	ds_read_b64 v[16:17], v37 offset:19584
	ds_read_b64 v[18:19], v37 offset:21760
	ds_read_b64 v[20:21], v37 offset:23936
	ds_read_b64 v[22:23], v37 offset:26112
	ds_read_b64 v[24:25], v37 offset:34816
	ds_read_b64 v[26:27], v37 offset:36992
	ds_read_b64 v[28:29], v37 offset:39168
	ds_read_b64 v[30:31], v37 offset:41344
	ds_read_b64 v[82:83], v37 offset:43520
	ds_read_b64 v[84:85], v37 offset:45696
	ds_read_b64 v[118:119], v37 offset:47872
	ds_read_b64 v[120:121], v37 offset:50048
	ds_read_b64 v[122:123], v37 offset:52224
	ds_read_b64 v[124:125], v37 offset:54400
	ds_read_b64 v[126:127], v37 offset:56576
	ds_read_b64 v[128:129], v37 offset:58752
	ds_read_b64 v[130:131], v37
	ds_read_b64 v[132:133], v37 offset:60928
	ds_read_b64 v[134:135], v37 offset:63104
	ds_read_b64 v[136:137], v37 offset:65280
	s_mov_b32 s11, s14
	s_waitcnt lgkmcnt(3)
	v_pk_add_f32 v[158:159], v[130:131], v[24:25]
	v_pk_add_f32 v[24:25], v[130:131], v[24:25] neg_lo:[0,1] neg_hi:[0,1]
	v_pk_add_f32 v[130:131], v[0:1], v[26:27]
	v_pk_add_f32 v[0:1], v[0:1], v[26:27] neg_lo:[0,1] neg_hi:[0,1]
	s_mov_b32 s13, s86
	v_pk_mul_f32 v[26:27], v[0:1], s[16:17]
	s_mov_b32 s4, s21
	v_pk_fma_f32 v[0:1], v[0:1], s[6:7], v[26:27] op_sel:[0,0,1] op_sel_hi:[1,0,0]
	v_pk_add_f32 v[26:27], v[2:3], v[28:29]
	v_pk_add_f32 v[2:3], v[2:3], v[28:29] neg_lo:[0,1] neg_hi:[0,1]
	s_mov_b32 s35, s30
	v_pk_mul_f32 v[28:29], v[2:3], s[18:19]
	s_mov_b32 s8, s19
	v_pk_fma_f32 v[2:3], v[2:3], s[30:31], v[28:29] op_sel:[0,0,1] op_sel_hi:[1,0,0]
	v_pk_add_f32 v[28:29], v[4:5], v[30:31]
	v_pk_add_f32 v[4:5], v[4:5], v[30:31] neg_lo:[0,1] neg_hi:[0,1]
	s_mov_b32 s77, s6
	v_pk_mul_f32 v[30:31], v[4:5], s[20:21]
	s_mov_b32 s28, s17
	v_pk_fma_f32 v[4:5], v[4:5], s[86:87], v[30:31] op_sel:[0,0,1] op_sel_hi:[1,0,0]
	v_pk_add_f32 v[30:31], v[6:7], v[82:83]
	v_pk_add_f32 v[6:7], v[6:7], v[82:83] neg_lo:[0,1] neg_hi:[0,1]
	v_add_u32_e32 v47, 0x10780, v37
	v_pk_mul_f32 v[82:83], v[6:7], s[10:11]
	ds_read_b64 v[138:139], v37 offset:28288
	ds_read_b64 v[140:141], v37 offset:30464
	ds_read_b64 v[142:143], v37 offset:32640
	ds_read_b64 v[144:145], v47
	v_pk_fma_f32 v[6:7], v[6:7], s[14:15], v[82:83] op_sel:[0,0,1] op_sel_hi:[1,0,0]
	v_pk_add_f32 v[82:83], v[8:9], v[84:85]
	v_pk_add_f32 v[8:9], v[8:9], v[84:85] neg_lo:[0,1] neg_hi:[0,1]
	s_nop 0
	v_pk_mul_f32 v[84:85], v[8:9], s[12:13]
	s_nop 0
	v_pk_fma_f32 v[8:9], v[8:9], s[4:5], v[84:85] op_sel:[0,0,1] op_sel_hi:[1,0,0]
	v_pk_add_f32 v[84:85], v[10:11], v[118:119]
	v_pk_add_f32 v[10:11], v[10:11], v[118:119] neg_lo:[0,1] neg_hi:[0,1]
	s_nop 0
	v_pk_mul_f32 v[118:119], v[10:11], s[34:35]
	s_nop 0
	v_pk_fma_f32 v[10:11], v[10:11], s[8:9], v[118:119] op_sel:[0,0,1] op_sel_hi:[1,0,0]
	v_pk_add_f32 v[118:119], v[12:13], v[120:121]
	v_pk_add_f32 v[12:13], v[12:13], v[120:121] neg_lo:[0,1] neg_hi:[0,1]
	s_nop 0
	v_pk_mul_f32 v[120:121], v[12:13], s[76:77]
	s_nop 0
	v_pk_fma_f32 v[12:13], v[12:13], s[28:29], v[120:121] op_sel:[0,0,1] op_sel_hi:[1,0,0]
	v_pk_add_f32 v[120:121], v[14:15], v[122:123]
	v_pk_add_f32 v[14:15], v[14:15], v[122:123] neg_lo:[0,1] neg_hi:[0,1]
	v_pk_add_f32 v[122:123], v[16:17], v[124:125]
	v_pk_add_f32 v[16:17], v[16:17], v[124:125] neg_lo:[0,1] neg_hi:[0,1]
	s_nop 0
	v_pk_mul_f32 v[124:125], v[16:17], s[76:77]
	s_nop 0
	v_pk_fma_f32 v[16:17], v[16:17], s[28:29], v[124:125] op_sel:[0,0,1] op_sel_hi:[1,0,0] neg_lo:[1,0,0] neg_hi:[1,0,0]
	v_pk_add_f32 v[124:125], v[18:19], v[126:127]
	v_pk_add_f32 v[18:19], v[18:19], v[126:127] neg_lo:[0,1] neg_hi:[0,1]
	s_nop 0
	v_pk_mul_f32 v[126:127], v[18:19], s[34:35]
	s_nop 0
	v_pk_fma_f32 v[18:19], v[18:19], s[8:9], v[126:127] op_sel:[0,0,1] op_sel_hi:[1,0,0] neg_lo:[1,0,0] neg_hi:[1,0,0]
	v_pk_add_f32 v[126:127], v[20:21], v[128:129]
	v_pk_add_f32 v[20:21], v[20:21], v[128:129] neg_lo:[0,1] neg_hi:[0,1]
	s_nop 0
	v_pk_mul_f32 v[128:129], v[20:21], s[12:13]
	s_nop 0
	v_pk_fma_f32 v[20:21], v[20:21], s[4:5], v[128:129] op_sel:[0,0,1] op_sel_hi:[1,0,0] neg_lo:[1,0,0] neg_hi:[1,0,0]
	s_waitcnt lgkmcnt(6)
	v_pk_add_f32 v[128:129], v[22:23], v[132:133]
	v_pk_add_f32 v[22:23], v[22:23], v[132:133] neg_lo:[0,1] neg_hi:[0,1]
	s_nop 0
	v_pk_mul_f32 v[132:133], v[22:23], s[10:11]
	s_nop 0
	v_pk_fma_f32 v[22:23], v[22:23], s[14:15], v[132:133] op_sel:[0,0,1] op_sel_hi:[1,0,0] neg_lo:[1,0,0] neg_hi:[1,0,0]
	s_waitcnt lgkmcnt(3)
	v_pk_add_f32 v[132:133], v[138:139], v[134:135]
	v_pk_add_f32 v[134:135], v[138:139], v[134:135] neg_lo:[0,1] neg_hi:[0,1]
	s_nop 0
	v_pk_mul_f32 v[138:139], v[134:135], s[20:21]
	s_nop 0
	v_pk_fma_f32 v[134:135], v[134:135], s[86:87], v[138:139] op_sel:[0,0,1] op_sel_hi:[1,0,0] neg_lo:[1,0,0] neg_hi:[1,0,0]
	s_waitcnt lgkmcnt(2)
	v_pk_add_f32 v[138:139], v[140:141], v[136:137]
	v_pk_add_f32 v[136:137], v[140:141], v[136:137] neg_lo:[0,1] neg_hi:[0,1]
	s_nop 0
	v_pk_mul_f32 v[140:141], v[136:137], s[18:19]
	s_nop 0
	v_pk_fma_f32 v[136:137], v[136:137], s[30:31], v[140:141] op_sel:[0,0,1] op_sel_hi:[1,0,0] neg_lo:[1,0,0] neg_hi:[1,0,0]
	s_waitcnt lgkmcnt(0)
	v_pk_add_f32 v[140:141], v[142:143], v[144:145]
	v_pk_add_f32 v[142:143], v[142:143], v[144:145] neg_lo:[0,1] neg_hi:[0,1]
	s_nop 0
	v_pk_mul_f32 v[144:145], v[142:143], s[16:17]
	s_nop 0
	v_pk_fma_f32 v[142:143], v[142:143], s[6:7], v[144:145] op_sel:[0,0,1] op_sel_hi:[1,0,0] neg_lo:[1,0,0] neg_hi:[1,0,0]
	v_pk_add_f32 v[144:145], v[158:159], v[120:121]
	v_pk_add_f32 v[120:121], v[158:159], v[120:121] neg_lo:[0,1] neg_hi:[0,1]
	v_pk_add_f32 v[158:159], v[130:131], v[122:123]
	v_pk_add_f32 v[122:123], v[130:131], v[122:123] neg_lo:[0,1] neg_hi:[0,1]
	s_nop 0
	v_pk_mul_f32 v[130:131], v[122:123], s[18:19]
	s_nop 0
	v_pk_fma_f32 v[122:123], v[122:123], s[30:31], v[130:131] op_sel:[0,0,1] op_sel_hi:[1,0,0]
	v_pk_add_f32 v[130:131], v[26:27], v[124:125]
	v_pk_add_f32 v[26:27], v[26:27], v[124:125] neg_lo:[0,1] neg_hi:[0,1]
	s_nop 0
	v_pk_mul_f32 v[124:125], v[26:27], s[10:11]
	s_nop 0
	v_pk_fma_f32 v[26:27], v[26:27], s[14:15], v[124:125] op_sel:[0,0,1] op_sel_hi:[1,0,0]
	v_pk_add_f32 v[124:125], v[28:29], v[126:127]
	v_pk_add_f32 v[28:29], v[28:29], v[126:127] neg_lo:[0,1] neg_hi:[0,1]
	s_nop 0
	v_pk_mul_f32 v[126:127], v[28:29], s[34:35]
	s_nop 0
	v_pk_fma_f32 v[28:29], v[28:29], s[8:9], v[126:127] op_sel:[0,0,1] op_sel_hi:[1,0,0]
	v_pk_add_f32 v[126:127], v[30:31], v[128:129]
	v_pk_add_f32 v[30:31], v[30:31], v[128:129] neg_lo:[0,1] neg_hi:[0,1]
	v_pk_add_f32 v[128:129], v[82:83], v[132:133]
	v_pk_add_f32 v[82:83], v[82:83], v[132:133] neg_lo:[0,1] neg_hi:[0,1]
	s_nop 0
	v_pk_mul_f32 v[132:133], v[82:83], s[34:35]
	s_nop 0
	v_pk_fma_f32 v[82:83], v[82:83], s[8:9], v[132:133] op_sel:[0,0,1] op_sel_hi:[1,0,0] neg_lo:[1,0,0] neg_hi:[1,0,0]
	v_pk_add_f32 v[132:133], v[84:85], v[138:139]
	v_pk_add_f32 v[84:85], v[84:85], v[138:139] neg_lo:[0,1] neg_hi:[0,1]
	s_nop 0
	v_pk_mul_f32 v[138:139], v[84:85], s[10:11]
	s_nop 0
	v_pk_fma_f32 v[84:85], v[84:85], s[14:15], v[138:139] op_sel:[0,0,1] op_sel_hi:[1,0,0] neg_lo:[1,0,0] neg_hi:[1,0,0]
	v_pk_add_f32 v[138:139], v[118:119], v[140:141]
	v_pk_add_f32 v[118:119], v[118:119], v[140:141] neg_lo:[0,1] neg_hi:[0,1]
	s_nop 0
	v_pk_mul_f32 v[140:141], v[118:119], s[18:19]
	s_nop 0
	v_pk_fma_f32 v[118:119], v[118:119], s[30:31], v[140:141] op_sel:[0,0,1] op_sel_hi:[1,0,0] neg_lo:[1,0,0] neg_hi:[1,0,0]
	v_pk_add_f32 v[140:141], v[24:25], v[14:15] op_sel:[0,1] op_sel_hi:[1,0] neg_hi:[0,1]
	v_pk_add_f32 v[14:15], v[24:25], v[14:15] op_sel:[0,1] op_sel_hi:[1,0] neg_lo:[0,1]
	v_pk_add_f32 v[24:25], v[0:1], v[16:17]
	v_pk_add_f32 v[0:1], v[0:1], v[16:17] neg_lo:[0,1] neg_hi:[0,1]
	s_nop 0
	v_pk_mul_f32 v[16:17], v[0:1], s[18:19]
	s_nop 0
	v_pk_fma_f32 v[0:1], v[0:1], s[30:31], v[16:17] op_sel:[0,0,1] op_sel_hi:[1,0,0]
	v_pk_add_f32 v[16:17], v[2:3], v[18:19]
	v_pk_add_f32 v[2:3], v[2:3], v[18:19] neg_lo:[0,1] neg_hi:[0,1]
	s_nop 0
	v_pk_mul_f32 v[18:19], v[2:3], s[10:11]
	s_nop 0
	v_pk_fma_f32 v[2:3], v[2:3], s[14:15], v[18:19] op_sel:[0,0,1] op_sel_hi:[1,0,0]
	v_pk_add_f32 v[18:19], v[4:5], v[20:21]
	v_pk_add_f32 v[4:5], v[4:5], v[20:21] neg_lo:[0,1] neg_hi:[0,1]
	s_nop 0
	v_pk_mul_f32 v[20:21], v[4:5], s[34:35]
	s_nop 0
	v_pk_fma_f32 v[4:5], v[4:5], s[8:9], v[20:21] op_sel:[0,0,1] op_sel_hi:[1,0,0]
	v_pk_add_f32 v[20:21], v[6:7], v[22:23]
	v_pk_add_f32 v[6:7], v[6:7], v[22:23] neg_lo:[0,1] neg_hi:[0,1]
	v_pk_add_f32 v[22:23], v[8:9], v[134:135]
	v_pk_add_f32 v[8:9], v[8:9], v[134:135] neg_lo:[0,1] neg_hi:[0,1]
	s_nop 0
	v_pk_mul_f32 v[134:135], v[8:9], s[34:35]
	s_nop 0
	v_pk_fma_f32 v[8:9], v[8:9], s[8:9], v[134:135] op_sel:[0,0,1] op_sel_hi:[1,0,0] neg_lo:[1,0,0] neg_hi:[1,0,0]
	v_pk_add_f32 v[134:135], v[10:11], v[136:137]
	v_pk_add_f32 v[10:11], v[10:11], v[136:137] neg_lo:[0,1] neg_hi:[0,1]
	s_nop 0
	v_pk_mul_f32 v[136:137], v[10:11], s[10:11]
	s_nop 0
	v_pk_fma_f32 v[10:11], v[10:11], s[14:15], v[136:137] op_sel:[0,0,1] op_sel_hi:[1,0,0] neg_lo:[1,0,0] neg_hi:[1,0,0]
	v_pk_add_f32 v[136:137], v[12:13], v[142:143]
	v_pk_add_f32 v[12:13], v[12:13], v[142:143] neg_lo:[0,1] neg_hi:[0,1]
	s_nop 0
	v_pk_mul_f32 v[142:143], v[12:13], s[18:19]
	s_nop 0
	v_pk_fma_f32 v[12:13], v[12:13], s[30:31], v[142:143] op_sel:[0,0,1] op_sel_hi:[1,0,0] neg_lo:[1,0,0] neg_hi:[1,0,0]
	v_pk_add_f32 v[142:143], v[144:145], v[126:127]
	v_pk_add_f32 v[126:127], v[144:145], v[126:127] neg_lo:[0,1] neg_hi:[0,1]
	v_pk_add_f32 v[144:145], v[158:159], v[128:129]
	v_pk_add_f32 v[128:129], v[158:159], v[128:129] neg_lo:[0,1] neg_hi:[0,1]
	s_nop 0
	v_pk_mul_f32 v[158:159], v[128:129], s[10:11]
	s_nop 0
	v_pk_fma_f32 v[128:129], v[128:129], s[14:15], v[158:159] op_sel:[0,0,1] op_sel_hi:[1,0,0]
	v_pk_add_f32 v[158:159], v[130:131], v[132:133]
	v_pk_add_f32 v[130:131], v[130:131], v[132:133] neg_lo:[0,1] neg_hi:[0,1]
	v_pk_add_f32 v[132:133], v[124:125], v[138:139]
	v_pk_add_f32 v[124:125], v[124:125], v[138:139] neg_lo:[0,1] neg_hi:[0,1]
	s_nop 0
	v_pk_mul_f32 v[138:139], v[124:125], s[10:11]
	s_nop 0
	v_pk_fma_f32 v[124:125], v[124:125], s[14:15], v[138:139] op_sel:[0,0,1] op_sel_hi:[1,0,0] neg_lo:[1,0,0] neg_hi:[1,0,0]
	v_pk_add_f32 v[138:139], v[120:121], v[30:31] op_sel:[0,1] op_sel_hi:[1,0] neg_hi:[0,1]
	v_pk_add_f32 v[30:31], v[120:121], v[30:31] op_sel:[0,1] op_sel_hi:[1,0] neg_lo:[0,1]
	v_pk_add_f32 v[120:121], v[122:123], v[82:83]
	v_pk_add_f32 v[82:83], v[122:123], v[82:83] neg_lo:[0,1] neg_hi:[0,1]
	v_pk_add_f32 v[160:161], v[128:129], v[124:125]
	v_pk_mul_f32 v[122:123], v[82:83], s[10:11]
	v_pk_add_f32 v[124:125], v[128:129], v[124:125] neg_lo:[0,1] neg_hi:[0,1]
	v_pk_fma_f32 v[82:83], v[82:83], s[14:15], v[122:123] op_sel:[0,0,1] op_sel_hi:[1,0,0]
	v_pk_add_f32 v[122:123], v[26:27], v[84:85]
	v_pk_add_f32 v[26:27], v[26:27], v[84:85] neg_lo:[0,1] neg_hi:[0,1]
	v_pk_add_f32 v[84:85], v[28:29], v[118:119]
	v_pk_add_f32 v[28:29], v[28:29], v[118:119] neg_lo:[0,1] neg_hi:[0,1]
	s_nop 0
	v_pk_mul_f32 v[118:119], v[28:29], s[10:11]
	v_pk_add_f32 v[166:167], v[120:121], v[84:85]
	v_pk_fma_f32 v[28:29], v[28:29], s[14:15], v[118:119] op_sel:[0,0,1] op_sel_hi:[1,0,0] neg_lo:[1,0,0] neg_hi:[1,0,0]
	v_pk_add_f32 v[118:119], v[140:141], v[20:21]
	v_pk_add_f32 v[20:21], v[140:141], v[20:21] neg_lo:[0,1] neg_hi:[0,1]
	v_pk_add_f32 v[140:141], v[24:25], v[22:23]
	v_pk_add_f32 v[22:23], v[24:25], v[22:23] neg_lo:[0,1] neg_hi:[0,1]
	v_pk_add_f32 v[84:85], v[120:121], v[84:85] neg_lo:[0,1] neg_hi:[0,1]
	v_pk_mul_f32 v[24:25], v[22:23], s[10:11]
	v_pk_add_f32 v[168:169], v[30:31], v[26:27] op_sel:[0,1] op_sel_hi:[1,0] neg_hi:[0,1]
	v_pk_fma_f32 v[22:23], v[22:23], s[14:15], v[24:25] op_sel:[0,0,1] op_sel_hi:[1,0,0]
	v_pk_add_f32 v[24:25], v[16:17], v[134:135]
	v_pk_add_f32 v[16:17], v[16:17], v[134:135] neg_lo:[0,1] neg_hi:[0,1]
	v_pk_add_f32 v[134:135], v[18:19], v[136:137]
	v_pk_add_f32 v[18:19], v[18:19], v[136:137] neg_lo:[0,1] neg_hi:[0,1]
	s_nop 0
	v_pk_mul_f32 v[136:137], v[18:19], s[10:11]
	v_pk_add_f32 v[26:27], v[30:31], v[26:27] op_sel:[0,1] op_sel_hi:[1,0] neg_lo:[0,1]
	v_pk_fma_f32 v[18:19], v[18:19], s[14:15], v[136:137] op_sel:[0,0,1] op_sel_hi:[1,0,0] neg_lo:[1,0,0] neg_hi:[1,0,0]
	v_pk_add_f32 v[136:137], v[14:15], v[6:7] op_sel:[0,1] op_sel_hi:[1,0] neg_hi:[0,1]
	v_pk_add_f32 v[6:7], v[14:15], v[6:7] op_sel:[0,1] op_sel_hi:[1,0] neg_lo:[0,1]
	v_pk_add_f32 v[14:15], v[0:1], v[8:9]
	v_pk_add_f32 v[0:1], v[0:1], v[8:9] neg_lo:[0,1] neg_hi:[0,1]
	v_pk_add_f32 v[30:31], v[82:83], v[28:29]
	v_pk_mul_f32 v[8:9], v[0:1], s[10:11]
	v_pk_add_f32 v[28:29], v[82:83], v[28:29] neg_lo:[0,1] neg_hi:[0,1]
	v_pk_fma_f32 v[0:1], v[0:1], s[14:15], v[8:9] op_sel:[0,0,1] op_sel_hi:[1,0,0]
	v_pk_add_f32 v[8:9], v[2:3], v[10:11]
	v_pk_add_f32 v[2:3], v[2:3], v[10:11] neg_lo:[0,1] neg_hi:[0,1]
	v_pk_add_f32 v[10:11], v[4:5], v[12:13]
	v_pk_add_f32 v[4:5], v[4:5], v[12:13] neg_lo:[0,1] neg_hi:[0,1]
	s_nop 0
	v_pk_mul_f32 v[12:13], v[4:5], s[10:11]
	v_pk_add_f32 v[170:171], v[118:119], v[24:25]
	v_pk_fma_f32 v[4:5], v[4:5], s[14:15], v[12:13] op_sel:[0,0,1] op_sel_hi:[1,0,0] neg_lo:[1,0,0] neg_hi:[1,0,0]
	v_pk_add_f32 v[12:13], v[142:143], v[158:159]
	v_pk_add_f32 v[142:143], v[142:143], v[158:159] neg_lo:[0,1] neg_hi:[0,1]
	v_pk_add_f32 v[158:159], v[144:145], v[132:133]
	v_pk_add_f32 v[132:133], v[144:145], v[132:133] neg_lo:[0,1] neg_hi:[0,1]
	v_pk_add_f32 v[182:183], v[118:119], v[24:25] neg_lo:[0,1] neg_hi:[0,1]
	v_pk_add_f32 v[184:185], v[140:141], v[134:135]
	v_pk_add_f32 v[24:25], v[140:141], v[134:135] neg_lo:[0,1] neg_hi:[0,1]
	v_pk_add_f32 v[140:141], v[20:21], v[16:17] op_sel:[0,1] op_sel_hi:[1,0] neg_hi:[0,1]
	v_pk_add_f32 v[186:187], v[20:21], v[16:17] op_sel:[0,1] op_sel_hi:[1,0] neg_lo:[0,1]
	v_pk_add_f32 v[16:17], v[22:23], v[18:19] neg_lo:[0,1] neg_hi:[0,1]
	v_pk_add_f32 v[192:193], v[136:137], v[8:9]
	v_pk_add_f32 v[194:195], v[136:137], v[8:9] neg_lo:[0,1] neg_hi:[0,1]
	v_pk_add_f32 v[8:9], v[14:15], v[10:11] neg_lo:[0,1] neg_hi:[0,1]
	v_pk_add_f32 v[198:199], v[6:7], v[2:3] op_sel:[0,1] op_sel_hi:[1,0] neg_hi:[0,1]
	v_pk_add_f32 v[200:201], v[6:7], v[2:3] op_sel:[0,1] op_sel_hi:[1,0] neg_lo:[0,1]
	v_pk_add_f32 v[2:3], v[0:1], v[4:5]
	v_pk_add_f32 v[0:1], v[0:1], v[4:5] neg_lo:[0,1] neg_hi:[0,1]
	v_pk_add_f32 v[144:145], v[126:127], v[130:131] op_sel:[0,1] op_sel_hi:[1,0] neg_hi:[0,1]
	v_pk_add_f32 v[130:131], v[126:127], v[130:131] op_sel:[0,1] op_sel_hi:[1,0] neg_lo:[0,1]
	v_pk_mul_f32 v[162:163], v[124:125], s[22:23]
	v_pk_add_f32 v[164:165], v[138:139], v[122:123]
	v_pk_add_f32 v[138:139], v[138:139], v[122:123] neg_lo:[0,1] neg_hi:[0,1]
	v_pk_mul_f32 v[82:83], v[28:29], s[22:23]
	v_pk_mul_f32 v[134:135], v[24:25], s[22:23]
	v_pk_add_f32 v[188:189], v[22:23], v[18:19]
	v_pk_mul_f32 v[190:191], v[16:17], s[22:23]
	v_pk_add_f32 v[136:137], v[14:15], v[10:11]
	v_pk_mul_f32 v[196:197], v[8:9], s[22:23]
	v_pk_mul_f32 v[202:203], v[0:1], s[22:23]
	v_pk_add_f32 v[28:29], v[12:13], v[158:159]
	v_pk_add_f32 v[128:129], v[12:13], v[158:159] neg_lo:[0,1] neg_hi:[0,1]
	v_pk_add_f32 v[24:25], v[142:143], v[132:133] op_sel:[0,1] op_sel_hi:[1,0] neg_hi:[0,1]
	v_pk_add_f32 v[126:127], v[142:143], v[132:133] op_sel:[0,1] op_sel_hi:[1,0] neg_lo:[0,1]
	v_pk_add_f32 v[20:21], v[144:145], v[160:161]
	v_pk_add_f32 v[124:125], v[144:145], v[160:161] neg_lo:[0,1] neg_hi:[0,1]
	v_pk_add_f32 v[16:17], v[130:131], v[162:163] op_sel:[0,1] op_sel_hi:[1,0]
	v_pk_add_f32 v[122:123], v[130:131], v[162:163] op_sel:[0,1] op_sel_hi:[1,0] neg_lo:[0,1] neg_hi:[0,1]
	v_pk_add_f32 v[12:13], v[164:165], v[166:167]
	v_pk_add_f32 v[120:121], v[164:165], v[166:167] neg_lo:[0,1] neg_hi:[0,1]
	v_pk_add_f32 v[8:9], v[138:139], v[84:85] op_sel:[0,1] op_sel_hi:[1,0] neg_hi:[0,1]
	v_pk_add_f32 v[118:119], v[138:139], v[84:85] op_sel:[0,1] op_sel_hi:[1,0] neg_lo:[0,1]
	v_pk_add_f32 v[4:5], v[168:169], v[30:31]
	v_pk_add_f32 v[84:85], v[168:169], v[30:31] neg_lo:[0,1] neg_hi:[0,1]
	v_pk_add_f32 v[0:1], v[26:27], v[82:83] op_sel:[0,1] op_sel_hi:[1,0]
	v_pk_add_f32 v[82:83], v[26:27], v[82:83] op_sel:[0,1] op_sel_hi:[1,0] neg_lo:[0,1] neg_hi:[0,1]
	v_pk_add_f32 v[30:31], v[170:171], v[184:185]
	v_pk_add_f32 v[144:145], v[170:171], v[184:185] neg_lo:[0,1] neg_hi:[0,1]
	v_pk_add_f32 v[26:27], v[182:183], v[134:135] op_sel:[0,1] op_sel_hi:[1,0]
	v_pk_add_f32 v[142:143], v[182:183], v[134:135] op_sel:[0,1] op_sel_hi:[1,0] neg_lo:[0,1] neg_hi:[0,1]
	v_pk_add_f32 v[22:23], v[140:141], v[188:189]
	v_pk_add_f32 v[140:141], v[140:141], v[188:189] neg_lo:[0,1] neg_hi:[0,1]
	v_pk_add_f32 v[18:19], v[186:187], v[190:191] op_sel:[0,1] op_sel_hi:[1,0]
	v_pk_add_f32 v[138:139], v[186:187], v[190:191] op_sel:[0,1] op_sel_hi:[1,0] neg_lo:[0,1] neg_hi:[0,1]
	v_pk_add_f32 v[14:15], v[192:193], v[136:137]
	v_pk_add_f32 v[136:137], v[192:193], v[136:137] neg_lo:[0,1] neg_hi:[0,1]
	v_pk_add_f32 v[10:11], v[194:195], v[196:197] op_sel:[0,1] op_sel_hi:[1,0]
	v_pk_add_f32 v[134:135], v[194:195], v[196:197] op_sel:[0,1] op_sel_hi:[1,0] neg_lo:[0,1] neg_hi:[0,1]
	v_pk_add_f32 v[6:7], v[198:199], v[2:3]
	v_pk_add_f32 v[132:133], v[198:199], v[2:3] neg_lo:[0,1] neg_hi:[0,1]
	v_pk_add_f32 v[2:3], v[200:201], v[202:203] op_sel:[0,1] op_sel_hi:[1,0]
	v_pk_add_f32 v[130:131], v[200:201], v[202:203] op_sel:[0,1] op_sel_hi:[1,0] neg_lo:[0,1] neg_hi:[0,1]

.LBB0_618:
	v_add_u32_e32 v160, 0x11000, v155
	v_lshlrev_b32_e32 v161, 3, v154
	v_add_u32_e32 v161, 0x2200, v161
	v_add_u32_e32 v162, 0x11100, v156
	v_cmp_ne_u32_e32 vcc, 0, v32
	v_cndmask_b32_e32 v163, 0, v154, vcc
	v_lshlrev_b32_e32 v163, 3, v163
	v_add_u32_e32 v163, 0x11000, v163
	ds_read_b64 v[214:215], v160 offset:0
	ds_read_b64 v[216:217], v163
	ds_read_b64 v[218:219], v122 offset:0
	ds_read_b64 v[220:221], v160 offset:4352
	ds_read_b64 v[222:223], v162 offset:60928
	ds_read_b64 v[224:225], v122 offset:4352
	ds_read_b64 v[226:227], v160 offset:8704
	ds_read_b64 v[228:229], v161 offset:52224
	ds_read_b64 v[230:231], v122 offset:8704
	ds_read_b64 v[232:233], v160 offset:13056
	ds_read_b64 v[234:235], v162 offset:52224
	ds_read_b64 v[236:237], v122 offset:13056
	s_waitcnt lgkmcnt(9)
	v_add_f32_e32 v164, v214, v216
	v_mul_f32_e32 v214, 0.5, v164
	v_sub_f32_e32 v164, v215, v217
	v_mul_f32_e32 v216, 0.5, v164
	v_pk_mul_f32 v[216:217], v[218:219], v[216:217] op_sel:[1,0] op_sel_hi:[0,0]
	v_pk_fma_f32 v[158:159], v[218:219], v[214:215], v[216:217] neg_lo:[0,0,1] neg_hi:[0,0,1]
	v_pk_fma_f32 v[214:215], v[218:219], v[214:215], v[216:217] op_sel_hi:[1,0,1]
	s_nop 0
	v_mov_b32_e32 v159, v215
	v_pk_mul_f32 v[218:219], v[158:159], s[24:25]
	ds_write_b64 v122, v[218:219] offset:0
	s_waitcnt lgkmcnt(7)
	v_add_f32_e32 v164, v220, v222
	v_mul_f32_e32 v220, 0.5, v164
	v_sub_f32_e32 v164, v221, v223
	v_mul_f32_e32 v222, 0.5, v164
	v_pk_mul_f32 v[222:223], v[224:225], v[222:223] op_sel:[1,0] op_sel_hi:[0,0]
	v_pk_fma_f32 v[158:159], v[224:225], v[220:221], v[222:223] neg_lo:[0,0,1] neg_hi:[0,0,1]
	v_pk_fma_f32 v[220:221], v[224:225], v[220:221], v[222:223] op_sel_hi:[1,0,1]
	s_nop 0
	v_mov_b32_e32 v159, v221
	v_pk_mul_f32 v[224:225], v[158:159], s[24:25]
	ds_write_b64 v122, v[224:225] offset:4352
	s_waitcnt lgkmcnt(5)
	v_add_f32_e32 v164, v226, v228
	v_mul_f32_e32 v226, 0.5, v164
	v_sub_f32_e32 v164, v227, v229
	v_mul_f32_e32 v228, 0.5, v164
	v_pk_mul_f32 v[228:229], v[230:231], v[228:229] op_sel:[1,0] op_sel_hi:[0,0]
	v_pk_fma_f32 v[158:159], v[230:231], v[226:227], v[228:229] neg_lo:[0,0,1] neg_hi:[0,0,1]
	v_pk_fma_f32 v[226:227], v[230:231], v[226:227], v[228:229] op_sel_hi:[1,0,1]
	s_nop 0
	v_mov_b32_e32 v159, v227
	v_pk_mul_f32 v[230:231], v[158:159], s[24:25]
	ds_write_b64 v122, v[230:231] offset:8704
	s_waitcnt lgkmcnt(3)
	v_add_f32_e32 v164, v232, v234
	v_mul_f32_e32 v232, 0.5, v164
	v_sub_f32_e32 v164, v233, v235
	v_mul_f32_e32 v234, 0.5, v164
	v_pk_mul_f32 v[234:235], v[236:237], v[234:235] op_sel:[1,0] op_sel_hi:[0,0]
	v_pk_fma_f32 v[158:159], v[236:237], v[232:233], v[234:235] neg_lo:[0,0,1] neg_hi:[0,0,1]
	v_pk_fma_f32 v[232:233], v[236:237], v[232:233], v[234:235] op_sel_hi:[1,0,1]
	s_nop 0
	v_mov_b32_e32 v159, v233
	v_pk_mul_f32 v[236:237], v[158:159], s[24:25]
	ds_write_b64 v122, v[236:237] offset:13056
	ds_read_b64 v[182:183], v160 offset:17408
	ds_read_b64 v[184:185], v161 offset:43520
	ds_read_b64 v[186:187], v122 offset:17408
	ds_read_b64 v[188:189], v160 offset:21760
	ds_read_b64 v[190:191], v162 offset:43520
	ds_read_b64 v[192:193], v122 offset:21760
	ds_read_b64 v[194:195], v160 offset:26112
	ds_read_b64 v[196:197], v161 offset:34816
	ds_read_b64 v[198:199], v122 offset:26112
	ds_read_b64 v[200:201], v160 offset:30464
	ds_read_b64 v[202:203], v162 offset:34816
	ds_read_b64 v[238:239], v122 offset:30464
	s_waitcnt lgkmcnt(9)
	v_add_f32_e32 v164, v182, v184
	v_mul_f32_e32 v182, 0.5, v164
	v_sub_f32_e32 v164, v183, v185
	v_mul_f32_e32 v184, 0.5, v164
	v_pk_mul_f32 v[184:185], v[186:187], v[184:185] op_sel:[1,0] op_sel_hi:[0,0]
	v_pk_fma_f32 v[158:159], v[186:187], v[182:183], v[184:185] neg_lo:[0,0,1] neg_hi:[0,0,1]
	v_pk_fma_f32 v[182:183], v[186:187], v[182:183], v[184:185] op_sel_hi:[1,0,1]
	s_nop 0
	v_mov_b32_e32 v159, v183
	v_pk_mul_f32 v[186:187], v[158:159], s[24:25]
	ds_write_b64 v122, v[186:187] offset:17408
	s_waitcnt lgkmcnt(7)
	v_add_f32_e32 v164, v188, v190
	v_mul_f32_e32 v188, 0.5, v164
	v_sub_f32_e32 v164, v189, v191
	v_mul_f32_e32 v190, 0.5, v164
	v_pk_mul_f32 v[190:191], v[192:193], v[190:191] op_sel:[1,0] op_sel_hi:[0,0]
	v_pk_fma_f32 v[158:159], v[192:193], v[188:189], v[190:191] neg_lo:[0,0,1] neg_hi:[0,0,1]
	v_pk_fma_f32 v[188:189], v[192:193], v[188:189], v[190:191] op_sel_hi:[1,0,1]
	s_nop 0
	v_mov_b32_e32 v159, v189
	v_pk_mul_f32 v[192:193], v[158:159], s[24:25]
	ds_write_b64 v122, v[192:193] offset:21760
	s_waitcnt lgkmcnt(5)
	v_add_f32_e32 v164, v194, v196
	v_mul_f32_e32 v194, 0.5, v164
	v_sub_f32_e32 v164, v195, v197
	v_mul_f32_e32 v196, 0.5, v164
	v_pk_mul_f32 v[196:197], v[198:199], v[196:197] op_sel:[1,0] op_sel_hi:[0,0]
	v_pk_fma_f32 v[158:159], v[198:199], v[194:195], v[196:197] neg_lo:[0,0,1] neg_hi:[0,0,1]
	v_pk_fma_f32 v[194:195], v[198:199], v[194:195], v[196:197] op_sel_hi:[1,0,1]
	s_nop 0
	v_mov_b32_e32 v159, v195
	v_pk_mul_f32 v[198:199], v[158:159], s[24:25]
	ds_write_b64 v122, v[198:199] offset:26112
	s_waitcnt lgkmcnt(3)
	v_add_f32_e32 v164, v200, v202
	v_mul_f32_e32 v200, 0.5, v164
	v_sub_f32_e32 v164, v201, v203
	v_mul_f32_e32 v202, 0.5, v164
	v_pk_mul_f32 v[202:203], v[238:239], v[202:203] op_sel:[1,0] op_sel_hi:[0,0]
	v_pk_fma_f32 v[158:159], v[238:239], v[200:201], v[202:203] neg_lo:[0,0,1] neg_hi:[0,0,1]
	v_pk_fma_f32 v[200:201], v[238:239], v[200:201], v[202:203] op_sel_hi:[1,0,1]
	s_nop 0
	v_mov_b32_e32 v159, v201
	v_pk_mul_f32 v[238:239], v[158:159], s[24:25]
	ds_write_b64 v122, v[238:239] offset:30464
	ds_read_b64 v[214:215], v160 offset:34816
	ds_read_b64 v[216:217], v161 offset:26112
	ds_read_b64 v[218:219], v122 offset:34816
	ds_read_b64 v[220:221], v160 offset:39168
	ds_read_b64 v[222:223], v162 offset:26112
	ds_read_b64 v[224:225], v122 offset:39168
	ds_read_b64 v[226:227], v160 offset:43520
	ds_read_b64 v[228:229], v161 offset:17408
	ds_read_b64 v[230:231], v122 offset:43520
	ds_read_b64 v[232:233], v160 offset:47872
	ds_read_b64 v[234:235], v162 offset:17408
	ds_read_b64 v[236:237], v122 offset:47872
	s_waitcnt lgkmcnt(9)
	v_add_f32_e32 v164, v214, v216
	v_mul_f32_e32 v214, 0.5, v164
	v_sub_f32_e32 v164, v215, v217
	v_mul_f32_e32 v216, 0.5, v164
	v_pk_mul_f32 v[216:217], v[218:219], v[216:217] op_sel:[1,0] op_sel_hi:[0,0]
	v_pk_fma_f32 v[158:159], v[218:219], v[214:215], v[216:217] neg_lo:[0,0,1] neg_hi:[0,0,1]
	v_pk_fma_f32 v[214:215], v[218:219], v[214:215], v[216:217] op_sel_hi:[1,0,1]
	s_nop 0
	v_mov_b32_e32 v159, v215
	v_pk_mul_f32 v[218:219], v[158:159], s[24:25]
	ds_write_b64 v122, v[218:219] offset:34816
	s_waitcnt lgkmcnt(7)
	v_add_f32_e32 v164, v220, v222
	v_mul_f32_e32 v220, 0.5, v164
	v_sub_f32_e32 v164, v221, v223
	v_mul_f32_e32 v222, 0.5, v164
	v_pk_mul_f32 v[222:223], v[224:225], v[222:223] op_sel:[1,0] op_sel_hi:[0,0]
	v_pk_fma_f32 v[158:159], v[224:225], v[220:221], v[222:223] neg_lo:[0,0,1] neg_hi:[0,0,1]
	v_pk_fma_f32 v[220:221], v[224:225], v[220:221], v[222:223] op_sel_hi:[1,0,1]
	s_nop 0
	v_mov_b32_e32 v159, v221
	v_pk_mul_f32 v[224:225], v[158:159], s[24:25]
	ds_write_b64 v122, v[224:225] offset:39168
	s_waitcnt lgkmcnt(5)
	v_add_f32_e32 v164, v226, v228
	v_mul_f32_e32 v226, 0.5, v164
	v_sub_f32_e32 v164, v227, v229
	v_mul_f32_e32 v228, 0.5, v164
	v_pk_mul_f32 v[228:229], v[230:231], v[228:229] op_sel:[1,0] op_sel_hi:[0,0]
	v_pk_fma_f32 v[158:159], v[230:231], v[226:227], v[228:229] neg_lo:[0,0,1] neg_hi:[0,0,1]
	v_pk_fma_f32 v[226:227], v[230:231], v[226:227], v[228:229] op_sel_hi:[1,0,1]
	s_nop 0
	v_mov_b32_e32 v159, v227
	v_pk_mul_f32 v[230:231], v[158:159], s[24:25]
	ds_write_b64 v122, v[230:231] offset:43520
	s_waitcnt lgkmcnt(3)
	v_add_f32_e32 v164, v232, v234
	v_mul_f32_e32 v232, 0.5, v164
	v_sub_f32_e32 v164, v233, v235
	v_mul_f32_e32 v234, 0.5, v164
	v_pk_mul_f32 v[234:235], v[236:237], v[234:235] op_sel:[1,0] op_sel_hi:[0,0]
	v_pk_fma_f32 v[158:159], v[236:237], v[232:233], v[234:235] neg_lo:[0,0,1] neg_hi:[0,0,1]
	v_pk_fma_f32 v[232:233], v[236:237], v[232:233], v[234:235] op_sel_hi:[1,0,1]
	s_nop 0
	v_mov_b32_e32 v159, v233
	v_pk_mul_f32 v[236:237], v[158:159], s[24:25]
	ds_write_b64 v122, v[236:237] offset:47872
	ds_read_b64 v[182:183], v160 offset:52224
	ds_read_b64 v[184:185], v161 offset:8704
	ds_read_b64 v[186:187], v122 offset:52224
	ds_read_b64 v[188:189], v160 offset:56576
	ds_read_b64 v[190:191], v162 offset:8704
	ds_read_b64 v[192:193], v122 offset:56576
	ds_read_b64 v[194:195], v160 offset:60928
	ds_read_b64 v[196:197], v161 offset:0
	ds_read_b64 v[198:199], v122 offset:60928
	ds_read_b64 v[200:201], v160 offset:65280
	ds_read_b64 v[202:203], v162 offset:0
	ds_read_b64 v[238:239], v122 offset:65280
	s_waitcnt lgkmcnt(9)
	v_add_f32_e32 v164, v182, v184
	v_mul_f32_e32 v182, 0.5, v164
	v_sub_f32_e32 v164, v183, v185
	v_mul_f32_e32 v184, 0.5, v164
	v_pk_mul_f32 v[184:185], v[186:187], v[184:185] op_sel:[1,0] op_sel_hi:[0,0]
	v_pk_fma_f32 v[158:159], v[186:187], v[182:183], v[184:185] neg_lo:[0,0,1] neg_hi:[0,0,1]
	v_pk_fma_f32 v[182:183], v[186:187], v[182:183], v[184:185] op_sel_hi:[1,0,1]
	s_nop 0
	v_mov_b32_e32 v159, v183
	v_pk_mul_f32 v[186:187], v[158:159], s[24:25]
	ds_write_b64 v122, v[186:187] offset:52224
	s_waitcnt lgkmcnt(7)
	v_add_f32_e32 v164, v188, v190
	v_mul_f32_e32 v188, 0.5, v164
	v_sub_f32_e32 v164, v189, v191
	v_mul_f32_e32 v190, 0.5, v164
	v_pk_mul_f32 v[190:191], v[192:193], v[190:191] op_sel:[1,0] op_sel_hi:[0,0]
	v_pk_fma_f32 v[158:159], v[192:193], v[188:189], v[190:191] neg_lo:[0,0,1] neg_hi:[0,0,1]
	v_pk_fma_f32 v[188:189], v[192:193], v[188:189], v[190:191] op_sel_hi:[1,0,1]
	s_nop 0
	v_mov_b32_e32 v159, v189
	v_pk_mul_f32 v[192:193], v[158:159], s[24:25]
	ds_write_b64 v122, v[192:193] offset:56576
	s_waitcnt lgkmcnt(5)
	v_add_f32_e32 v164, v194, v196
	v_mul_f32_e32 v194, 0.5, v164
	v_sub_f32_e32 v164, v195, v197
	v_mul_f32_e32 v196, 0.5, v164
	v_pk_mul_f32 v[196:197], v[198:199], v[196:197] op_sel:[1,0] op_sel_hi:[0,0]
	v_pk_fma_f32 v[158:159], v[198:199], v[194:195], v[196:197] neg_lo:[0,0,1] neg_hi:[0,0,1]
	v_pk_fma_f32 v[194:195], v[198:199], v[194:195], v[196:197] op_sel_hi:[1,0,1]
	s_nop 0
	v_mov_b32_e32 v159, v195
	v_pk_mul_f32 v[198:199], v[158:159], s[24:25]
	ds_write_b64 v122, v[198:199] offset:60928
	s_waitcnt lgkmcnt(3)
	v_add_f32_e32 v164, v200, v202
	v_mul_f32_e32 v200, 0.5, v164
	v_sub_f32_e32 v164, v201, v203
	v_mul_f32_e32 v202, 0.5, v164
	v_pk_mul_f32 v[202:203], v[238:239], v[202:203] op_sel:[1,0] op_sel_hi:[0,0]
	v_pk_fma_f32 v[158:159], v[238:239], v[200:201], v[202:203] neg_lo:[0,0,1] neg_hi:[0,0,1]
	v_pk_fma_f32 v[200:201], v[238:239], v[200:201], v[202:203] op_sel_hi:[1,0,1]
	s_nop 0
	v_mov_b32_e32 v159, v201
	v_pk_mul_f32 v[238:239], v[158:159], s[24:25]
	ds_write_b64 v122, v[238:239] offset:65280
	s_mov_b32 s4, 16
	s_cmp_lg_u32 s4, 16
	s_waitcnt lgkmcnt(0)
	s_barrier
	s_and_saveexec_b64 s[28:29], s[40:41]
	s_cbranch_execz .LBB0_621
	ds_read_b64 v[0:1], v153
	ds_read_b64 v[2:3], v153 offset:2176
	ds_read_b64 v[4:5], v153 offset:4352
	ds_read_b64 v[6:7], v153 offset:6528
	ds_read_b64 v[8:9], v153 offset:8704
	ds_read_b64 v[10:11], v153 offset:10880
	ds_read_b64 v[12:13], v153 offset:13056
	ds_read_b64 v[14:15], v153 offset:15232
	ds_read_b64 v[16:17], v153 offset:17408
	ds_read_b64 v[18:19], v153 offset:19584
	ds_read_b64 v[20:21], v153 offset:21760
	ds_read_b64 v[22:23], v153 offset:23936
	ds_read_b64 v[24:25], v153 offset:26112
	ds_read_b64 v[26:27], v153 offset:28288
	ds_read_b64 v[28:29], v153 offset:30464
	ds_read_b64 v[30:31], v153 offset:32640
	ds_read_b64 v[86:87], v153 offset:34816
	ds_read_b64 v[92:93], v153 offset:41344
	ds_read_b64 v[94:95], v153 offset:43520
	ds_read_b64 v[96:97], v153 offset:45696
	ds_read_b64 v[98:99], v153 offset:47872
	ds_read_b64 v[100:101], v153 offset:50048
	ds_read_b64 v[102:103], v153 offset:52224
	ds_read_b64 v[104:105], v153 offset:54400
	ds_read_b64 v[106:107], v153 offset:56576
	ds_read_b64 v[108:109], v153 offset:58752
	ds_read_b64 v[110:111], v153 offset:60928
	ds_read_b64 v[112:113], v153 offset:63104
	ds_read_b64 v[114:115], v153 offset:65280
	ds_read_b64 v[116:117], v153 offset:36992
	ds_read_b64 v[118:119], v153 offset:39168
	ds_read_b64 v[120:121], v33
	s_waitcnt lgkmcnt(14)
	v_pk_add_f32 v[124:125], v[0:1], v[86:87]
	v_pk_add_f32 v[0:1], v[0:1], v[86:87] neg_lo:[0,1] neg_hi:[0,1]
	s_waitcnt lgkmcnt(2)
	v_pk_add_f32 v[86:87], v[2:3], v[116:117]
	v_pk_add_f32 v[2:3], v[2:3], v[116:117] neg_lo:[0,1] neg_hi:[0,1]
	s_mov_b32 s11, s14
	v_pk_mul_f32 v[116:117], v[2:3], s[16:17]
	s_mov_b32 s13, s86
	v_pk_fma_f32 v[2:3], v[2:3], s[6:7], v[116:117] op_sel:[0,0,1] op_sel_hi:[1,0,0]
	s_waitcnt lgkmcnt(1)
	v_pk_add_f32 v[116:117], v[4:5], v[118:119]
	v_pk_add_f32 v[4:5], v[4:5], v[118:119] neg_lo:[0,1] neg_hi:[0,1]
	s_mov_b32 s4, s21
	v_pk_mul_f32 v[118:119], v[4:5], s[18:19]
	s_mov_b32 s35, s30
	v_pk_fma_f32 v[4:5], v[4:5], s[30:31], v[118:119] op_sel:[0,0,1] op_sel_hi:[1,0,0]
	v_pk_add_f32 v[118:119], v[6:7], v[92:93]
	v_pk_add_f32 v[6:7], v[6:7], v[92:93] neg_lo:[0,1] neg_hi:[0,1]
	s_mov_b32 s8, s19
	v_pk_mul_f32 v[92:93], v[6:7], s[20:21]
	s_mov_b32 s77, s6
	v_pk_fma_f32 v[6:7], v[6:7], s[86:87], v[92:93] op_sel:[0,0,1] op_sel_hi:[1,0,0]
	v_pk_add_f32 v[92:93], v[8:9], v[94:95]
	v_pk_add_f32 v[8:9], v[8:9], v[94:95] neg_lo:[0,1] neg_hi:[0,1]
	s_mov_b32 s26, s17
	v_pk_mul_f32 v[94:95], v[8:9], s[10:11]
	s_nop 0
	v_pk_fma_f32 v[8:9], v[8:9], s[14:15], v[94:95] op_sel:[0,0,1] op_sel_hi:[1,0,0]
	v_pk_add_f32 v[94:95], v[10:11], v[96:97]
	v_pk_add_f32 v[10:11], v[10:11], v[96:97] neg_lo:[0,1] neg_hi:[0,1]
	s_nop 0
	v_pk_mul_f32 v[96:97], v[10:11], s[12:13]
	s_nop 0
	v_pk_fma_f32 v[10:11], v[10:11], s[4:5], v[96:97] op_sel:[0,0,1] op_sel_hi:[1,0,0]
	v_pk_add_f32 v[96:97], v[12:13], v[98:99]
	v_pk_add_f32 v[12:13], v[12:13], v[98:99] neg_lo:[0,1] neg_hi:[0,1]
	s_nop 0
	v_pk_mul_f32 v[98:99], v[12:13], s[34:35]
	s_nop 0
	v_pk_fma_f32 v[12:13], v[12:13], s[8:9], v[98:99] op_sel:[0,0,1] op_sel_hi:[1,0,0]
	v_pk_add_f32 v[98:99], v[14:15], v[100:101]
	v_pk_add_f32 v[14:15], v[14:15], v[100:101] neg_lo:[0,1] neg_hi:[0,1]
	s_nop 0
	v_pk_mul_f32 v[100:101], v[14:15], s[76:77]
	s_nop 0
	v_pk_fma_f32 v[14:15], v[14:15], s[26:27], v[100:101] op_sel:[0,0,1] op_sel_hi:[1,0,0]
	v_pk_add_f32 v[100:101], v[16:17], v[102:103]
	v_pk_add_f32 v[16:17], v[16:17], v[102:103] neg_lo:[0,1] neg_hi:[0,1]
	v_pk_add_f32 v[102:103], v[18:19], v[104:105]
	v_pk_add_f32 v[18:19], v[18:19], v[104:105] neg_lo:[0,1] neg_hi:[0,1]
	s_nop 0
	v_pk_mul_f32 v[104:105], v[18:19], s[76:77]
	s_nop 0
	v_pk_fma_f32 v[18:19], v[18:19], s[26:27], v[104:105] op_sel:[0,0,1] op_sel_hi:[1,0,0] neg_lo:[1,0,0] neg_hi:[1,0,0]
	v_pk_add_f32 v[104:105], v[20:21], v[106:107]
	v_pk_add_f32 v[20:21], v[20:21], v[106:107] neg_lo:[0,1] neg_hi:[0,1]
	s_nop 0
	v_pk_mul_f32 v[106:107], v[20:21], s[34:35]
	s_nop 0
	v_pk_fma_f32 v[20:21], v[20:21], s[8:9], v[106:107] op_sel:[0,0,1] op_sel_hi:[1,0,0] neg_lo:[1,0,0] neg_hi:[1,0,0]
	v_pk_add_f32 v[106:107], v[22:23], v[108:109]
	v_pk_add_f32 v[22:23], v[22:23], v[108:109] neg_lo:[0,1] neg_hi:[0,1]
	s_nop 0
	v_pk_mul_f32 v[108:109], v[22:23], s[12:13]
	s_nop 0
	v_pk_fma_f32 v[22:23], v[22:23], s[4:5], v[108:109] op_sel:[0,0,1] op_sel_hi:[1,0,0] neg_lo:[1,0,0] neg_hi:[1,0,0]
	v_pk_add_f32 v[108:109], v[24:25], v[110:111]
	v_pk_add_f32 v[24:25], v[24:25], v[110:111] neg_lo:[0,1] neg_hi:[0,1]
	s_nop 0
	v_pk_mul_f32 v[110:111], v[24:25], s[10:11]
	s_nop 0
	v_pk_fma_f32 v[24:25], v[24:25], s[14:15], v[110:111] op_sel:[0,0,1] op_sel_hi:[1,0,0] neg_lo:[1,0,0] neg_hi:[1,0,0]
	v_pk_add_f32 v[110:111], v[26:27], v[112:113]
	v_pk_add_f32 v[26:27], v[26:27], v[112:113] neg_lo:[0,1] neg_hi:[0,1]
	s_nop 0
	v_pk_mul_f32 v[112:113], v[26:27], s[20:21]
	s_nop 0
	v_pk_fma_f32 v[26:27], v[26:27], s[86:87], v[112:113] op_sel:[0,0,1] op_sel_hi:[1,0,0] neg_lo:[1,0,0] neg_hi:[1,0,0]
	v_pk_add_f32 v[112:113], v[28:29], v[114:115]
	v_pk_add_f32 v[28:29], v[28:29], v[114:115] neg_lo:[0,1] neg_hi:[0,1]
	s_nop 0
	v_pk_mul_f32 v[114:115], v[28:29], s[18:19]
	s_nop 0
	v_pk_fma_f32 v[28:29], v[28:29], s[30:31], v[114:115] op_sel:[0,0,1] op_sel_hi:[1,0,0] neg_lo:[1,0,0] neg_hi:[1,0,0]
	s_waitcnt lgkmcnt(0)
	v_pk_add_f32 v[114:115], v[30:31], v[120:121]
	v_pk_add_f32 v[30:31], v[30:31], v[120:121] neg_lo:[0,1] neg_hi:[0,1]
	s_nop 0
	v_pk_mul_f32 v[120:121], v[30:31], s[16:17]
	s_nop 0
	v_pk_fma_f32 v[30:31], v[30:31], s[6:7], v[120:121] op_sel:[0,0,1] op_sel_hi:[1,0,0] neg_lo:[1,0,0] neg_hi:[1,0,0]
	v_pk_add_f32 v[120:121], v[124:125], v[100:101]
	v_pk_add_f32 v[100:101], v[124:125], v[100:101] neg_lo:[0,1] neg_hi:[0,1]
	v_pk_add_f32 v[124:125], v[86:87], v[102:103]
	v_pk_add_f32 v[86:87], v[86:87], v[102:103] neg_lo:[0,1] neg_hi:[0,1]
	s_nop 0
	v_pk_mul_f32 v[102:103], v[86:87], s[18:19]
	s_nop 0
	v_pk_fma_f32 v[86:87], v[86:87], s[30:31], v[102:103] op_sel:[0,0,1] op_sel_hi:[1,0,0]
	v_pk_add_f32 v[102:103], v[116:117], v[104:105]
	v_pk_add_f32 v[104:105], v[116:117], v[104:105] neg_lo:[0,1] neg_hi:[0,1]
	s_nop 0
	v_pk_mul_f32 v[116:117], v[104:105], s[10:11]
	s_nop 0
	v_pk_fma_f32 v[104:105], v[104:105], s[14:15], v[116:117] op_sel:[0,0,1] op_sel_hi:[1,0,0]
	v_pk_add_f32 v[116:117], v[118:119], v[106:107]
	v_pk_add_f32 v[106:107], v[118:119], v[106:107] neg_lo:[0,1] neg_hi:[0,1]
	s_nop 0
	v_pk_mul_f32 v[118:119], v[106:107], s[34:35]
	s_nop 0
	v_pk_fma_f32 v[106:107], v[106:107], s[8:9], v[118:119] op_sel:[0,0,1] op_sel_hi:[1,0,0]
	v_pk_add_f32 v[118:119], v[92:93], v[108:109]
	v_pk_add_f32 v[92:93], v[92:93], v[108:109] neg_lo:[0,1] neg_hi:[0,1]
	v_pk_add_f32 v[108:109], v[94:95], v[110:111]
	v_pk_add_f32 v[94:95], v[94:95], v[110:111] neg_lo:[0,1] neg_hi:[0,1]
	s_nop 0
	v_pk_mul_f32 v[110:111], v[94:95], s[34:35]
	s_nop 0
	v_pk_fma_f32 v[94:95], v[94:95], s[8:9], v[110:111] op_sel:[0,0,1] op_sel_hi:[1,0,0] neg_lo:[1,0,0] neg_hi:[1,0,0]
	v_pk_add_f32 v[110:111], v[96:97], v[112:113]
	v_pk_add_f32 v[96:97], v[96:97], v[112:113] neg_lo:[0,1] neg_hi:[0,1]
	s_nop 0
	v_pk_mul_f32 v[112:113], v[96:97], s[10:11]
	s_nop 0
	v_pk_fma_f32 v[96:97], v[96:97], s[14:15], v[112:113] op_sel:[0,0,1] op_sel_hi:[1,0,0] neg_lo:[1,0,0] neg_hi:[1,0,0]
	v_pk_add_f32 v[112:113], v[98:99], v[114:115]
	v_pk_add_f32 v[98:99], v[98:99], v[114:115] neg_lo:[0,1] neg_hi:[0,1]
	s_nop 0
	v_pk_mul_f32 v[114:115], v[98:99], s[18:19]
	s_nop 0
	v_pk_fma_f32 v[98:99], v[98:99], s[30:31], v[114:115] op_sel:[0,0,1] op_sel_hi:[1,0,0] neg_lo:[1,0,0] neg_hi:[1,0,0]
	v_pk_add_f32 v[114:115], v[0:1], v[16:17] op_sel:[0,1] op_sel_hi:[1,0] neg_hi:[0,1]
	v_pk_add_f32 v[0:1], v[0:1], v[16:17] op_sel:[0,1] op_sel_hi:[1,0] neg_lo:[0,1]
	v_pk_add_f32 v[16:17], v[2:3], v[18:19]
	v_pk_add_f32 v[2:3], v[2:3], v[18:19] neg_lo:[0,1] neg_hi:[0,1]
	s_nop 0
	v_pk_mul_f32 v[18:19], v[2:3], s[18:19]
	s_nop 0
	v_pk_fma_f32 v[2:3], v[2:3], s[30:31], v[18:19] op_sel:[0,0,1] op_sel_hi:[1,0,0]
	v_pk_add_f32 v[18:19], v[4:5], v[20:21]
	v_pk_add_f32 v[4:5], v[4:5], v[20:21] neg_lo:[0,1] neg_hi:[0,1]
	s_nop 0
	v_pk_mul_f32 v[20:21], v[4:5], s[10:11]
	s_nop 0
	v_pk_fma_f32 v[4:5], v[4:5], s[14:15], v[20:21] op_sel:[0,0,1] op_sel_hi:[1,0,0]
	v_pk_add_f32 v[20:21], v[6:7], v[22:23]
	v_pk_add_f32 v[6:7], v[6:7], v[22:23] neg_lo:[0,1] neg_hi:[0,1]
	s_nop 0
	v_pk_mul_f32 v[22:23], v[6:7], s[34:35]
	s_nop 0
	v_pk_fma_f32 v[6:7], v[6:7], s[8:9], v[22:23] op_sel:[0,0,1] op_sel_hi:[1,0,0]
	v_pk_add_f32 v[22:23], v[8:9], v[24:25]
	v_pk_add_f32 v[8:9], v[8:9], v[24:25] neg_lo:[0,1] neg_hi:[0,1]
	v_pk_add_f32 v[24:25], v[10:11], v[26:27]
	v_pk_add_f32 v[10:11], v[10:11], v[26:27] neg_lo:[0,1] neg_hi:[0,1]
	s_nop 0
	v_pk_mul_f32 v[26:27], v[10:11], s[34:35]
	s_nop 0
	v_pk_fma_f32 v[10:11], v[10:11], s[8:9], v[26:27] op_sel:[0,0,1] op_sel_hi:[1,0,0] neg_lo:[1,0,0] neg_hi:[1,0,0]
	v_pk_add_f32 v[26:27], v[12:13], v[28:29]
	v_pk_add_f32 v[12:13], v[12:13], v[28:29] neg_lo:[0,1] neg_hi:[0,1]
	s_nop 0
	v_pk_mul_f32 v[28:29], v[12:13], s[10:11]
	s_nop 0
	v_pk_fma_f32 v[12:13], v[12:13], s[14:15], v[28:29] op_sel:[0,0,1] op_sel_hi:[1,0,0] neg_lo:[1,0,0] neg_hi:[1,0,0]
	v_pk_add_f32 v[28:29], v[14:15], v[30:31]
	v_pk_add_f32 v[14:15], v[14:15], v[30:31] neg_lo:[0,1] neg_hi:[0,1]
	s_nop 0
	v_pk_mul_f32 v[30:31], v[14:15], s[18:19]
	s_nop 0
	v_pk_fma_f32 v[14:15], v[14:15], s[30:31], v[30:31] op_sel:[0,0,1] op_sel_hi:[1,0,0] neg_lo:[1,0,0] neg_hi:[1,0,0]
	v_pk_add_f32 v[30:31], v[120:121], v[118:119]
	v_pk_add_f32 v[118:119], v[120:121], v[118:119] neg_lo:[0,1] neg_hi:[0,1]
	v_pk_add_f32 v[120:121], v[124:125], v[108:109]
	v_pk_add_f32 v[108:109], v[124:125], v[108:109] neg_lo:[0,1] neg_hi:[0,1]
	s_nop 0
	v_pk_mul_f32 v[124:125], v[108:109], s[10:11]
	s_nop 0
	v_pk_fma_f32 v[108:109], v[108:109], s[14:15], v[124:125] op_sel:[0,0,1] op_sel_hi:[1,0,0]
	v_pk_add_f32 v[124:125], v[102:103], v[110:111]
	v_pk_add_f32 v[102:103], v[102:103], v[110:111] neg_lo:[0,1] neg_hi:[0,1]
	v_pk_add_f32 v[110:111], v[116:117], v[112:113]
	v_pk_add_f32 v[112:113], v[116:117], v[112:113] neg_lo:[0,1] neg_hi:[0,1]
	s_nop 0
	v_pk_mul_f32 v[116:117], v[112:113], s[10:11]
	s_nop 0
	v_pk_fma_f32 v[112:113], v[112:113], s[14:15], v[116:117] op_sel:[0,0,1] op_sel_hi:[1,0,0] neg_lo:[1,0,0] neg_hi:[1,0,0]
	v_pk_add_f32 v[116:117], v[100:101], v[92:93] op_sel:[0,1] op_sel_hi:[1,0] neg_hi:[0,1]
	v_pk_add_f32 v[92:93], v[100:101], v[92:93] op_sel:[0,1] op_sel_hi:[1,0] neg_lo:[0,1]
	v_pk_add_f32 v[100:101], v[86:87], v[94:95]
	v_pk_add_f32 v[86:87], v[86:87], v[94:95] neg_lo:[0,1] neg_hi:[0,1]
	v_pk_add_f32 v[126:127], v[108:109], v[112:113]
	v_pk_mul_f32 v[94:95], v[86:87], s[10:11]
	s_nop 0
	v_pk_fma_f32 v[86:87], v[86:87], s[14:15], v[94:95] op_sel:[0,0,1] op_sel_hi:[1,0,0]
	v_pk_add_f32 v[94:95], v[104:105], v[96:97]
	v_pk_add_f32 v[96:97], v[104:105], v[96:97] neg_lo:[0,1] neg_hi:[0,1]
	v_pk_add_f32 v[104:105], v[106:107], v[98:99]
	v_pk_add_f32 v[98:99], v[106:107], v[98:99] neg_lo:[0,1] neg_hi:[0,1]
	s_nop 0
	v_pk_mul_f32 v[106:107], v[98:99], s[10:11]
	v_pk_add_f32 v[130:131], v[92:93], v[96:97] op_sel:[0,1] op_sel_hi:[1,0] neg_hi:[0,1]
	v_pk_fma_f32 v[98:99], v[98:99], s[14:15], v[106:107] op_sel:[0,0,1] op_sel_hi:[1,0,0] neg_lo:[1,0,0] neg_hi:[1,0,0]
	v_pk_add_f32 v[106:107], v[114:115], v[22:23]
	v_pk_add_f32 v[22:23], v[114:115], v[22:23] neg_lo:[0,1] neg_hi:[0,1]
	v_pk_add_f32 v[114:115], v[16:17], v[24:25]
	v_pk_add_f32 v[16:17], v[16:17], v[24:25] neg_lo:[0,1] neg_hi:[0,1]
	v_pk_add_f32 v[132:133], v[92:93], v[96:97] op_sel:[0,1] op_sel_hi:[1,0] neg_lo:[0,1]
	v_pk_mul_f32 v[24:25], v[16:17], s[10:11]
	v_pk_add_f32 v[92:93], v[86:87], v[98:99]
	v_pk_fma_f32 v[16:17], v[16:17], s[14:15], v[24:25] op_sel:[0,0,1] op_sel_hi:[1,0,0]
	v_pk_add_f32 v[24:25], v[18:19], v[26:27]
	v_pk_add_f32 v[18:19], v[18:19], v[26:27] neg_lo:[0,1] neg_hi:[0,1]
	v_pk_add_f32 v[26:27], v[20:21], v[28:29]
	v_pk_add_f32 v[20:21], v[20:21], v[28:29] neg_lo:[0,1] neg_hi:[0,1]
	s_nop 0
	v_pk_mul_f32 v[28:29], v[20:21], s[10:11]
	v_pk_add_f32 v[86:87], v[86:87], v[98:99] neg_lo:[0,1] neg_hi:[0,1]
	v_pk_fma_f32 v[20:21], v[20:21], s[14:15], v[28:29] op_sel:[0,0,1] op_sel_hi:[1,0,0] neg_lo:[1,0,0] neg_hi:[1,0,0]
	v_pk_add_f32 v[28:29], v[0:1], v[8:9] op_sel:[0,1] op_sel_hi:[1,0] neg_hi:[0,1]
	v_pk_add_f32 v[0:1], v[0:1], v[8:9] op_sel:[0,1] op_sel_hi:[1,0] neg_lo:[0,1]
	v_pk_add_f32 v[8:9], v[2:3], v[10:11]
	v_pk_add_f32 v[2:3], v[2:3], v[10:11] neg_lo:[0,1] neg_hi:[0,1]
	v_pk_add_f32 v[134:135], v[106:107], v[24:25]
	v_pk_mul_f32 v[10:11], v[2:3], s[10:11]
	v_pk_add_f32 v[106:107], v[106:107], v[24:25] neg_lo:[0,1] neg_hi:[0,1]
	v_pk_fma_f32 v[2:3], v[2:3], s[14:15], v[10:11] op_sel:[0,0,1] op_sel_hi:[1,0,0]
	v_pk_add_f32 v[10:11], v[4:5], v[12:13]
	v_pk_add_f32 v[4:5], v[4:5], v[12:13] neg_lo:[0,1] neg_hi:[0,1]
	v_pk_add_f32 v[12:13], v[6:7], v[14:15]
	v_pk_add_f32 v[6:7], v[6:7], v[14:15] neg_lo:[0,1] neg_hi:[0,1]
	s_nop 0
	v_pk_mul_f32 v[14:15], v[6:7], s[10:11]
	v_pk_add_f32 v[24:25], v[114:115], v[26:27] neg_lo:[0,1] neg_hi:[0,1]
	v_pk_fma_f32 v[6:7], v[6:7], s[14:15], v[14:15] op_sel:[0,0,1] op_sel_hi:[1,0,0] neg_lo:[1,0,0] neg_hi:[1,0,0]
	v_pk_add_f32 v[14:15], v[30:31], v[124:125]
	v_pk_add_f32 v[30:31], v[30:31], v[124:125] neg_lo:[0,1] neg_hi:[0,1]
	v_pk_add_f32 v[124:125], v[120:121], v[110:111]
	v_pk_add_f32 v[110:111], v[120:121], v[110:111] neg_lo:[0,1] neg_hi:[0,1]
	v_pk_add_f32 v[120:121], v[118:119], v[102:103] op_sel:[0,1] op_sel_hi:[1,0] neg_hi:[0,1]
	v_pk_add_f32 v[118:119], v[118:119], v[102:103] op_sel:[0,1] op_sel_hi:[1,0] neg_lo:[0,1]
	v_pk_add_f32 v[102:103], v[108:109], v[112:113] neg_lo:[0,1] neg_hi:[0,1]
	v_pk_add_f32 v[112:113], v[116:117], v[94:95]
	v_pk_add_f32 v[94:95], v[116:117], v[94:95] neg_lo:[0,1] neg_hi:[0,1]
	v_pk_add_f32 v[116:117], v[100:101], v[104:105]
	v_pk_add_f32 v[100:101], v[100:101], v[104:105] neg_lo:[0,1] neg_hi:[0,1]
	v_pk_add_f32 v[138:139], v[22:23], v[18:19] op_sel:[0,1] op_sel_hi:[1,0] neg_hi:[0,1]
	v_pk_add_f32 v[140:141], v[22:23], v[18:19] op_sel:[0,1] op_sel_hi:[1,0] neg_lo:[0,1]
	v_pk_add_f32 v[18:19], v[16:17], v[20:21]
	v_pk_add_f32 v[16:17], v[16:17], v[20:21] neg_lo:[0,1] neg_hi:[0,1]
	v_pk_add_f32 v[144:145], v[28:29], v[10:11]
	v_pk_add_f32 v[158:159], v[28:29], v[10:11] neg_lo:[0,1] neg_hi:[0,1]
	v_pk_add_f32 v[10:11], v[8:9], v[12:13]
	v_pk_add_f32 v[8:9], v[8:9], v[12:13] neg_lo:[0,1] neg_hi:[0,1]
	v_pk_add_f32 v[162:163], v[0:1], v[4:5] op_sel:[0,1] op_sel_hi:[1,0] neg_hi:[0,1]
	v_pk_add_f32 v[164:165], v[0:1], v[4:5] op_sel:[0,1] op_sel_hi:[1,0] neg_lo:[0,1]
	v_pk_add_f32 v[0:1], v[2:3], v[6:7] neg_lo:[0,1] neg_hi:[0,1]
	v_pk_mul_f32 v[108:109], v[102:103], s[22:23]
	v_pk_mul_f32 v[128:129], v[100:101], s[22:23]
	v_pk_add_f32 v[136:137], v[114:115], v[26:27]
	v_pk_mul_f32 v[114:115], v[24:25], s[22:23]
	v_pk_mul_f32 v[142:143], v[16:17], s[22:23]
	v_pk_mul_f32 v[160:161], v[8:9], s[22:23]
	v_pk_add_f32 v[166:167], v[2:3], v[6:7]
	v_pk_mul_f32 v[168:169], v[0:1], s[22:23]
	v_pk_add_f32 v[28:29], v[14:15], v[124:125]
	v_pk_add_f32 v[104:105], v[14:15], v[124:125] neg_lo:[0,1] neg_hi:[0,1]
	v_pk_add_f32 v[24:25], v[30:31], v[110:111] op_sel:[0,1] op_sel_hi:[1,0] neg_hi:[0,1]
	v_pk_add_f32 v[102:103], v[30:31], v[110:111] op_sel:[0,1] op_sel_hi:[1,0] neg_lo:[0,1]
	v_pk_add_f32 v[20:21], v[120:121], v[126:127]
	v_pk_add_f32 v[100:101], v[120:121], v[126:127] neg_lo:[0,1] neg_hi:[0,1]
	v_pk_add_f32 v[16:17], v[118:119], v[108:109] op_sel:[0,1] op_sel_hi:[1,0]
	v_pk_add_f32 v[98:99], v[118:119], v[108:109] op_sel:[0,1] op_sel_hi:[1,0] neg_lo:[0,1] neg_hi:[0,1]
	v_pk_add_f32 v[12:13], v[112:113], v[116:117]
	v_pk_add_f32 v[96:97], v[112:113], v[116:117] neg_lo:[0,1] neg_hi:[0,1]
	v_pk_add_f32 v[8:9], v[94:95], v[128:129] op_sel:[0,1] op_sel_hi:[1,0]
	v_pk_add_f32 v[94:95], v[94:95], v[128:129] op_sel:[0,1] op_sel_hi:[1,0] neg_lo:[0,1] neg_hi:[0,1]
	v_pk_add_f32 v[4:5], v[130:131], v[92:93]
	v_pk_add_f32 v[92:93], v[130:131], v[92:93] neg_lo:[0,1] neg_hi:[0,1]
	v_pk_add_f32 v[0:1], v[132:133], v[86:87] op_sel:[0,1] op_sel_hi:[1,0] neg_hi:[0,1]
	v_pk_add_f32 v[86:87], v[132:133], v[86:87] op_sel:[0,1] op_sel_hi:[1,0] neg_lo:[0,1]
	v_pk_add_f32 v[30:31], v[134:135], v[136:137]
	v_pk_add_f32 v[120:121], v[134:135], v[136:137] neg_lo:[0,1] neg_hi:[0,1]
	v_pk_add_f32 v[26:27], v[106:107], v[114:115] op_sel:[0,1] op_sel_hi:[1,0]
	v_pk_add_f32 v[118:119], v[106:107], v[114:115] op_sel:[0,1] op_sel_hi:[1,0] neg_lo:[0,1] neg_hi:[0,1]
	v_pk_add_f32 v[22:23], v[138:139], v[18:19]
	v_pk_add_f32 v[116:117], v[138:139], v[18:19] neg_lo:[0,1] neg_hi:[0,1]
	v_pk_add_f32 v[18:19], v[140:141], v[142:143] op_sel:[0,1] op_sel_hi:[1,0]
	v_pk_add_f32 v[114:115], v[140:141], v[142:143] op_sel:[0,1] op_sel_hi:[1,0] neg_lo:[0,1] neg_hi:[0,1]
	v_pk_add_f32 v[14:15], v[144:145], v[10:11]
	v_pk_add_f32 v[112:113], v[144:145], v[10:11] neg_lo:[0,1] neg_hi:[0,1]
	v_pk_add_f32 v[10:11], v[158:159], v[160:161] op_sel:[0,1] op_sel_hi:[1,0]
	v_pk_add_f32 v[110:111], v[158:159], v[160:161] op_sel:[0,1] op_sel_hi:[1,0] neg_lo:[0,1] neg_hi:[0,1]
	v_pk_add_f32 v[6:7], v[162:163], v[166:167]
	v_pk_add_f32 v[108:109], v[162:163], v[166:167] neg_lo:[0,1] neg_hi:[0,1]
	v_pk_add_f32 v[2:3], v[164:165], v[168:169] op_sel:[0,1] op_sel_hi:[1,0]
	v_pk_add_f32 v[106:107], v[164:165], v[168:169] op_sel:[0,1] op_sel_hi:[1,0] neg_lo:[0,1] neg_hi:[0,1]

.LBB0_670:
	v_add_u32_e32 v160, 0x11000, v155
	v_lshlrev_b32_e32 v161, 3, v154
	v_add_u32_e32 v161, 0x2200, v161
	v_add_u32_e32 v162, 0x11100, v156
	v_cmp_ne_u32_e32 vcc, 0, v32
	v_cndmask_b32_e32 v163, 0, v154, vcc
	v_lshlrev_b32_e32 v163, 3, v163
	v_add_u32_e32 v163, 0x11000, v163
	ds_read_b64 v[214:215], v160 offset:0
	ds_read_b64 v[216:217], v163
	ds_read_b64 v[218:219], v155 offset:0
	ds_read_b64 v[220:221], v160 offset:4352
	ds_read_b64 v[222:223], v162 offset:60928
	ds_read_b64 v[224:225], v155 offset:4352
	ds_read_b64 v[226:227], v160 offset:8704
	ds_read_b64 v[228:229], v161 offset:52224
	ds_read_b64 v[230:231], v155 offset:8704
	ds_read_b64 v[232:233], v160 offset:13056
	ds_read_b64 v[234:235], v162 offset:52224
	ds_read_b64 v[236:237], v155 offset:13056
	s_waitcnt lgkmcnt(9)
	v_add_f32_e32 v164, v215, v217
	v_sub_f32_e32 v165, v214, v216
	v_mul_f32_e32 v216, 0.5, v164
	v_mul_f32_e32 v214, -0.5, v165
	v_pk_mul_f32 v[214:215], v[218:219], v[214:215] op_sel:[1,0] op_sel_hi:[0,0]
	v_pk_fma_f32 v[158:159], v[218:219], v[216:217], v[214:215] neg_lo:[0,0,1] neg_hi:[0,0,1]
	v_pk_fma_f32 v[216:217], v[218:219], v[216:217], v[214:215] op_sel_hi:[1,0,1]
	s_nop 0
	v_mov_b32_e32 v159, v217
	v_pk_mul_f32 v[218:219], v[158:159], s[24:25]
	ds_write_b64 v155, v[218:219] offset:0
	s_waitcnt lgkmcnt(7)
	v_add_f32_e32 v164, v221, v223
	v_sub_f32_e32 v165, v220, v222
	v_mul_f32_e32 v222, 0.5, v164
	v_mul_f32_e32 v220, -0.5, v165
	v_pk_mul_f32 v[220:221], v[224:225], v[220:221] op_sel:[1,0] op_sel_hi:[0,0]
	v_pk_fma_f32 v[158:159], v[224:225], v[222:223], v[220:221] neg_lo:[0,0,1] neg_hi:[0,0,1]
	v_pk_fma_f32 v[222:223], v[224:225], v[222:223], v[220:221] op_sel_hi:[1,0,1]
	s_nop 0
	v_mov_b32_e32 v159, v223
	v_pk_mul_f32 v[224:225], v[158:159], s[24:25]
	ds_write_b64 v155, v[224:225] offset:4352
	s_waitcnt lgkmcnt(5)
	v_add_f32_e32 v164, v227, v229
	v_sub_f32_e32 v165, v226, v228
	v_mul_f32_e32 v228, 0.5, v164
	v_mul_f32_e32 v226, -0.5, v165
	v_pk_mul_f32 v[226:227], v[230:231], v[226:227] op_sel:[1,0] op_sel_hi:[0,0]
	v_pk_fma_f32 v[158:159], v[230:231], v[228:229], v[226:227] neg_lo:[0,0,1] neg_hi:[0,0,1]
	v_pk_fma_f32 v[228:229], v[230:231], v[228:229], v[226:227] op_sel_hi:[1,0,1]
	s_nop 0
	v_mov_b32_e32 v159, v229
	v_pk_mul_f32 v[230:231], v[158:159], s[24:25]
	ds_write_b64 v155, v[230:231] offset:8704
	s_waitcnt lgkmcnt(3)
	v_add_f32_e32 v164, v233, v235
	v_sub_f32_e32 v165, v232, v234
	v_mul_f32_e32 v234, 0.5, v164
	v_mul_f32_e32 v232, -0.5, v165
	v_pk_mul_f32 v[232:233], v[236:237], v[232:233] op_sel:[1,0] op_sel_hi:[0,0]
	v_pk_fma_f32 v[158:159], v[236:237], v[234:235], v[232:233] neg_lo:[0,0,1] neg_hi:[0,0,1]
	v_pk_fma_f32 v[234:235], v[236:237], v[234:235], v[232:233] op_sel_hi:[1,0,1]
	s_nop 0
	v_mov_b32_e32 v159, v235
	v_pk_mul_f32 v[236:237], v[158:159], s[24:25]
	ds_write_b64 v155, v[236:237] offset:13056
	ds_read_b64 v[182:183], v160 offset:17408
	ds_read_b64 v[184:185], v161 offset:43520
	ds_read_b64 v[186:187], v155 offset:17408
	ds_read_b64 v[188:189], v160 offset:21760
	ds_read_b64 v[190:191], v162 offset:43520
	ds_read_b64 v[192:193], v155 offset:21760
	ds_read_b64 v[194:195], v160 offset:26112
	ds_read_b64 v[196:197], v161 offset:34816
	ds_read_b64 v[198:199], v155 offset:26112
	ds_read_b64 v[200:201], v160 offset:30464
	ds_read_b64 v[202:203], v162 offset:34816
	ds_read_b64 v[238:239], v155 offset:30464
	s_waitcnt lgkmcnt(9)
	v_add_f32_e32 v164, v183, v185
	v_sub_f32_e32 v165, v182, v184
	v_mul_f32_e32 v184, 0.5, v164
	v_mul_f32_e32 v182, -0.5, v165
	v_pk_mul_f32 v[182:183], v[186:187], v[182:183] op_sel:[1,0] op_sel_hi:[0,0]
	v_pk_fma_f32 v[158:159], v[186:187], v[184:185], v[182:183] neg_lo:[0,0,1] neg_hi:[0,0,1]
	v_pk_fma_f32 v[184:185], v[186:187], v[184:185], v[182:183] op_sel_hi:[1,0,1]
	s_nop 0
	v_mov_b32_e32 v159, v185
	v_pk_mul_f32 v[186:187], v[158:159], s[24:25]
	ds_write_b64 v155, v[186:187] offset:17408
	s_waitcnt lgkmcnt(7)
	v_add_f32_e32 v164, v189, v191
	v_sub_f32_e32 v165, v188, v190
	v_mul_f32_e32 v190, 0.5, v164
	v_mul_f32_e32 v188, -0.5, v165
	v_pk_mul_f32 v[188:189], v[192:193], v[188:189] op_sel:[1,0] op_sel_hi:[0,0]
	v_pk_fma_f32 v[158:159], v[192:193], v[190:191], v[188:189] neg_lo:[0,0,1] neg_hi:[0,0,1]
	v_pk_fma_f32 v[190:191], v[192:193], v[190:191], v[188:189] op_sel_hi:[1,0,1]
	s_nop 0
	v_mov_b32_e32 v159, v191
	v_pk_mul_f32 v[192:193], v[158:159], s[24:25]
	ds_write_b64 v155, v[192:193] offset:21760
	s_waitcnt lgkmcnt(5)
	v_add_f32_e32 v164, v195, v197
	v_sub_f32_e32 v165, v194, v196
	v_mul_f32_e32 v196, 0.5, v164
	v_mul_f32_e32 v194, -0.5, v165
	v_pk_mul_f32 v[194:195], v[198:199], v[194:195] op_sel:[1,0] op_sel_hi:[0,0]
	v_pk_fma_f32 v[158:159], v[198:199], v[196:197], v[194:195] neg_lo:[0,0,1] neg_hi:[0,0,1]
	v_pk_fma_f32 v[196:197], v[198:199], v[196:197], v[194:195] op_sel_hi:[1,0,1]
	s_nop 0
	v_mov_b32_e32 v159, v197
	v_pk_mul_f32 v[198:199], v[158:159], s[24:25]
	ds_write_b64 v155, v[198:199] offset:26112
	s_waitcnt lgkmcnt(3)
	v_add_f32_e32 v164, v201, v203
	v_sub_f32_e32 v165, v200, v202
	v_mul_f32_e32 v202, 0.5, v164
	v_mul_f32_e32 v200, -0.5, v165
	v_pk_mul_f32 v[200:201], v[238:239], v[200:201] op_sel:[1,0] op_sel_hi:[0,0]
	v_pk_fma_f32 v[158:159], v[238:239], v[202:203], v[200:201] neg_lo:[0,0,1] neg_hi:[0,0,1]
	v_pk_fma_f32 v[202:203], v[238:239], v[202:203], v[200:201] op_sel_hi:[1,0,1]
	s_nop 0
	v_mov_b32_e32 v159, v203
	v_pk_mul_f32 v[238:239], v[158:159], s[24:25]
	ds_write_b64 v155, v[238:239] offset:30464
	ds_read_b64 v[214:215], v160 offset:34816
	ds_read_b64 v[216:217], v161 offset:26112
	ds_read_b64 v[218:219], v155 offset:34816
	ds_read_b64 v[220:221], v160 offset:39168
	ds_read_b64 v[222:223], v162 offset:26112
	ds_read_b64 v[224:225], v155 offset:39168
	ds_read_b64 v[226:227], v160 offset:43520
	ds_read_b64 v[228:229], v161 offset:17408
	ds_read_b64 v[230:231], v155 offset:43520
	ds_read_b64 v[232:233], v160 offset:47872
	ds_read_b64 v[234:235], v162 offset:17408
	ds_read_b64 v[236:237], v155 offset:47872
	s_waitcnt lgkmcnt(9)
	v_add_f32_e32 v164, v215, v217
	v_sub_f32_e32 v165, v214, v216
	v_mul_f32_e32 v216, 0.5, v164
	v_mul_f32_e32 v214, -0.5, v165
	v_pk_mul_f32 v[214:215], v[218:219], v[214:215] op_sel:[1,0] op_sel_hi:[0,0]
	v_pk_fma_f32 v[158:159], v[218:219], v[216:217], v[214:215] neg_lo:[0,0,1] neg_hi:[0,0,1]
	v_pk_fma_f32 v[216:217], v[218:219], v[216:217], v[214:215] op_sel_hi:[1,0,1]
	s_nop 0
	v_mov_b32_e32 v159, v217
	v_pk_mul_f32 v[218:219], v[158:159], s[24:25]
	ds_write_b64 v155, v[218:219] offset:34816
	s_waitcnt lgkmcnt(7)
	v_add_f32_e32 v164, v221, v223
	v_sub_f32_e32 v165, v220, v222
	v_mul_f32_e32 v222, 0.5, v164
	v_mul_f32_e32 v220, -0.5, v165
	v_pk_mul_f32 v[220:221], v[224:225], v[220:221] op_sel:[1,0] op_sel_hi:[0,0]
	v_pk_fma_f32 v[158:159], v[224:225], v[222:223], v[220:221] neg_lo:[0,0,1] neg_hi:[0,0,1]
	v_pk_fma_f32 v[222:223], v[224:225], v[222:223], v[220:221] op_sel_hi:[1,0,1]
	s_nop 0
	v_mov_b32_e32 v159, v223
	v_pk_mul_f32 v[224:225], v[158:159], s[24:25]
	ds_write_b64 v155, v[224:225] offset:39168
	s_waitcnt lgkmcnt(5)
	v_add_f32_e32 v164, v227, v229
	v_sub_f32_e32 v165, v226, v228
	v_mul_f32_e32 v228, 0.5, v164
	v_mul_f32_e32 v226, -0.5, v165
	v_pk_mul_f32 v[226:227], v[230:231], v[226:227] op_sel:[1,0] op_sel_hi:[0,0]
	v_pk_fma_f32 v[158:159], v[230:231], v[228:229], v[226:227] neg_lo:[0,0,1] neg_hi:[0,0,1]
	v_pk_fma_f32 v[228:229], v[230:231], v[228:229], v[226:227] op_sel_hi:[1,0,1]
	s_nop 0
	v_mov_b32_e32 v159, v229
	v_pk_mul_f32 v[230:231], v[158:159], s[24:25]
	ds_write_b64 v155, v[230:231] offset:43520
	s_waitcnt lgkmcnt(3)
	v_add_f32_e32 v164, v233, v235
	v_sub_f32_e32 v165, v232, v234
	v_mul_f32_e32 v234, 0.5, v164
	v_mul_f32_e32 v232, -0.5, v165
	v_pk_mul_f32 v[232:233], v[236:237], v[232:233] op_sel:[1,0] op_sel_hi:[0,0]
	v_pk_fma_f32 v[158:159], v[236:237], v[234:235], v[232:233] neg_lo:[0,0,1] neg_hi:[0,0,1]
	v_pk_fma_f32 v[234:235], v[236:237], v[234:235], v[232:233] op_sel_hi:[1,0,1]
	s_nop 0
	v_mov_b32_e32 v159, v235
	v_pk_mul_f32 v[236:237], v[158:159], s[24:25]
	ds_write_b64 v155, v[236:237] offset:47872
	ds_read_b64 v[182:183], v160 offset:52224
	ds_read_b64 v[184:185], v161 offset:8704
	ds_read_b64 v[186:187], v155 offset:52224
	ds_read_b64 v[188:189], v160 offset:56576
	ds_read_b64 v[190:191], v162 offset:8704
	ds_read_b64 v[192:193], v155 offset:56576
	ds_read_b64 v[194:195], v160 offset:60928
	ds_read_b64 v[196:197], v161 offset:0
	ds_read_b64 v[198:199], v155 offset:60928
	ds_read_b64 v[200:201], v160 offset:65280
	ds_read_b64 v[202:203], v162 offset:0
	ds_read_b64 v[238:239], v155 offset:65280
	s_waitcnt lgkmcnt(9)
	v_add_f32_e32 v164, v183, v185
	v_sub_f32_e32 v165, v182, v184
	v_mul_f32_e32 v184, 0.5, v164
	v_mul_f32_e32 v182, -0.5, v165
	v_pk_mul_f32 v[182:183], v[186:187], v[182:183] op_sel:[1,0] op_sel_hi:[0,0]
	v_pk_fma_f32 v[158:159], v[186:187], v[184:185], v[182:183] neg_lo:[0,0,1] neg_hi:[0,0,1]
	v_pk_fma_f32 v[184:185], v[186:187], v[184:185], v[182:183] op_sel_hi:[1,0,1]
	s_nop 0
	v_mov_b32_e32 v159, v185
	v_pk_mul_f32 v[186:187], v[158:159], s[24:25]
	ds_write_b64 v155, v[186:187] offset:52224
	s_waitcnt lgkmcnt(7)
	v_add_f32_e32 v164, v189, v191
	v_sub_f32_e32 v165, v188, v190
	v_mul_f32_e32 v190, 0.5, v164
	v_mul_f32_e32 v188, -0.5, v165
	v_pk_mul_f32 v[188:189], v[192:193], v[188:189] op_sel:[1,0] op_sel_hi:[0,0]
	v_pk_fma_f32 v[158:159], v[192:193], v[190:191], v[188:189] neg_lo:[0,0,1] neg_hi:[0,0,1]
	v_pk_fma_f32 v[190:191], v[192:193], v[190:191], v[188:189] op_sel_hi:[1,0,1]
	s_nop 0
	v_mov_b32_e32 v159, v191
	v_pk_mul_f32 v[192:193], v[158:159], s[24:25]
	ds_write_b64 v155, v[192:193] offset:56576
	s_waitcnt lgkmcnt(5)
	v_add_f32_e32 v164, v195, v197
	v_sub_f32_e32 v165, v194, v196
	v_mul_f32_e32 v196, 0.5, v164
	v_mul_f32_e32 v194, -0.5, v165
	v_pk_mul_f32 v[194:195], v[198:199], v[194:195] op_sel:[1,0] op_sel_hi:[0,0]
	v_pk_fma_f32 v[158:159], v[198:199], v[196:197], v[194:195] neg_lo:[0,0,1] neg_hi:[0,0,1]
	v_pk_fma_f32 v[196:197], v[198:199], v[196:197], v[194:195] op_sel_hi:[1,0,1]
	s_nop 0
	v_mov_b32_e32 v159, v197
	v_pk_mul_f32 v[198:199], v[158:159], s[24:25]
	ds_write_b64 v155, v[198:199] offset:60928
	s_waitcnt lgkmcnt(3)
	v_add_f32_e32 v164, v201, v203
	v_sub_f32_e32 v165, v200, v202
	v_mul_f32_e32 v202, 0.5, v164
	v_mul_f32_e32 v200, -0.5, v165
	v_pk_mul_f32 v[200:201], v[238:239], v[200:201] op_sel:[1,0] op_sel_hi:[0,0]
	v_pk_fma_f32 v[158:159], v[238:239], v[202:203], v[200:201] neg_lo:[0,0,1] neg_hi:[0,0,1]
	v_pk_fma_f32 v[202:203], v[238:239], v[202:203], v[200:201] op_sel_hi:[1,0,1]
	s_nop 0
	v_mov_b32_e32 v159, v203
	v_pk_mul_f32 v[238:239], v[158:159], s[24:25]
	ds_write_b64 v155, v[238:239] offset:65280
	s_mov_b32 s4, 16
	s_cmp_lg_u32 s4, 16
	s_waitcnt lgkmcnt(0)
	s_barrier
	s_and_saveexec_b64 s[28:29], s[40:41]
	s_cbranch_execz .LBB0_673
	ds_read_b64 v[0:1], v153
	ds_read_b64 v[2:3], v153 offset:2176
	ds_read_b64 v[4:5], v153 offset:4352
	ds_read_b64 v[6:7], v153 offset:6528
	ds_read_b64 v[8:9], v153 offset:8704
	ds_read_b64 v[10:11], v153 offset:10880
	ds_read_b64 v[12:13], v153 offset:13056
	ds_read_b64 v[14:15], v153 offset:15232
	ds_read_b64 v[16:17], v153 offset:17408
	ds_read_b64 v[18:19], v153 offset:19584
	ds_read_b64 v[20:21], v153 offset:21760
	ds_read_b64 v[22:23], v153 offset:23936
	ds_read_b64 v[24:25], v153 offset:26112
	ds_read_b64 v[26:27], v153 offset:28288
	ds_read_b64 v[28:29], v153 offset:30464
	ds_read_b64 v[30:31], v153 offset:32640
	ds_read_b64 v[58:59], v153 offset:34816
	ds_read_b64 v[60:61], v153 offset:41344
	ds_read_b64 v[94:95], v153 offset:43520
	ds_read_b64 v[96:97], v153 offset:45696
	ds_read_b64 v[98:99], v153 offset:47872
	ds_read_b64 v[100:101], v153 offset:50048
	ds_read_b64 v[102:103], v153 offset:52224
	ds_read_b64 v[104:105], v153 offset:54400
	ds_read_b64 v[106:107], v153 offset:56576
	ds_read_b64 v[108:109], v153 offset:58752
	ds_read_b64 v[110:111], v153 offset:60928
	ds_read_b64 v[112:113], v153 offset:63104
	ds_read_b64 v[114:115], v153 offset:65280
	ds_read_b64 v[116:117], v153 offset:36992
	ds_read_b64 v[118:119], v153 offset:39168
	ds_read_b64 v[120:121], v33
	s_waitcnt lgkmcnt(14)
	v_pk_add_f32 v[124:125], v[0:1], v[58:59]
	v_pk_add_f32 v[0:1], v[0:1], v[58:59] neg_lo:[0,1] neg_hi:[0,1]
	s_waitcnt lgkmcnt(2)
	v_pk_add_f32 v[58:59], v[2:3], v[116:117]
	v_pk_add_f32 v[2:3], v[2:3], v[116:117] neg_lo:[0,1] neg_hi:[0,1]
	s_mov_b32 s11, s14
	v_pk_mul_f32 v[116:117], v[2:3], s[16:17]
	s_mov_b32 s13, s86
	v_pk_fma_f32 v[2:3], v[2:3], s[6:7], v[116:117] op_sel:[0,0,1] op_sel_hi:[1,0,0]
	s_waitcnt lgkmcnt(1)
	v_pk_add_f32 v[116:117], v[4:5], v[118:119]
	v_pk_add_f32 v[4:5], v[4:5], v[118:119] neg_lo:[0,1] neg_hi:[0,1]
	s_mov_b32 s4, s21
	v_pk_mul_f32 v[118:119], v[4:5], s[18:19]
	s_mov_b32 s35, s30
	v_pk_fma_f32 v[4:5], v[4:5], s[30:31], v[118:119] op_sel:[0,0,1] op_sel_hi:[1,0,0]
	v_pk_add_f32 v[118:119], v[6:7], v[60:61]
	v_pk_add_f32 v[6:7], v[6:7], v[60:61] neg_lo:[0,1] neg_hi:[0,1]
	s_mov_b32 s8, s19
	v_pk_mul_f32 v[60:61], v[6:7], s[20:21]
	s_mov_b32 s77, s6
	v_pk_fma_f32 v[6:7], v[6:7], s[86:87], v[60:61] op_sel:[0,0,1] op_sel_hi:[1,0,0]
	v_pk_add_f32 v[60:61], v[8:9], v[94:95]
	v_pk_add_f32 v[8:9], v[8:9], v[94:95] neg_lo:[0,1] neg_hi:[0,1]
	s_mov_b32 s26, s17
	v_pk_mul_f32 v[94:95], v[8:9], s[10:11]
	s_nop 0
	v_pk_fma_f32 v[8:9], v[8:9], s[14:15], v[94:95] op_sel:[0,0,1] op_sel_hi:[1,0,0]
	v_pk_add_f32 v[94:95], v[10:11], v[96:97]
	v_pk_add_f32 v[10:11], v[10:11], v[96:97] neg_lo:[0,1] neg_hi:[0,1]
	s_nop 0
	v_pk_mul_f32 v[96:97], v[10:11], s[12:13]
	s_nop 0
	v_pk_fma_f32 v[10:11], v[10:11], s[4:5], v[96:97] op_sel:[0,0,1] op_sel_hi:[1,0,0]
	v_pk_add_f32 v[96:97], v[12:13], v[98:99]
	v_pk_add_f32 v[12:13], v[12:13], v[98:99] neg_lo:[0,1] neg_hi:[0,1]
	s_nop 0
	v_pk_mul_f32 v[98:99], v[12:13], s[34:35]
	s_nop 0
	v_pk_fma_f32 v[12:13], v[12:13], s[8:9], v[98:99] op_sel:[0,0,1] op_sel_hi:[1,0,0]
	v_pk_add_f32 v[98:99], v[14:15], v[100:101]
	v_pk_add_f32 v[14:15], v[14:15], v[100:101] neg_lo:[0,1] neg_hi:[0,1]
	s_nop 0
	v_pk_mul_f32 v[100:101], v[14:15], s[76:77]
	s_nop 0
	v_pk_fma_f32 v[14:15], v[14:15], s[26:27], v[100:101] op_sel:[0,0,1] op_sel_hi:[1,0,0]
	v_pk_add_f32 v[100:101], v[16:17], v[102:103]
	v_pk_add_f32 v[16:17], v[16:17], v[102:103] neg_lo:[0,1] neg_hi:[0,1]
	v_pk_add_f32 v[102:103], v[18:19], v[104:105]
	v_pk_add_f32 v[18:19], v[18:19], v[104:105] neg_lo:[0,1] neg_hi:[0,1]
	s_nop 0
	v_pk_mul_f32 v[104:105], v[18:19], s[76:77]
	s_nop 0
	v_pk_fma_f32 v[18:19], v[18:19], s[26:27], v[104:105] op_sel:[0,0,1] op_sel_hi:[1,0,0] neg_lo:[1,0,0] neg_hi:[1,0,0]
	v_pk_add_f32 v[104:105], v[20:21], v[106:107]
	v_pk_add_f32 v[20:21], v[20:21], v[106:107] neg_lo:[0,1] neg_hi:[0,1]
	s_nop 0
	v_pk_mul_f32 v[106:107], v[20:21], s[34:35]
	s_nop 0
	v_pk_fma_f32 v[20:21], v[20:21], s[8:9], v[106:107] op_sel:[0,0,1] op_sel_hi:[1,0,0] neg_lo:[1,0,0] neg_hi:[1,0,0]
	v_pk_add_f32 v[106:107], v[22:23], v[108:109]
	v_pk_add_f32 v[22:23], v[22:23], v[108:109] neg_lo:[0,1] neg_hi:[0,1]
	s_nop 0
	v_pk_mul_f32 v[108:109], v[22:23], s[12:13]
	s_nop 0
	v_pk_fma_f32 v[22:23], v[22:23], s[4:5], v[108:109] op_sel:[0,0,1] op_sel_hi:[1,0,0] neg_lo:[1,0,0] neg_hi:[1,0,0]
	v_pk_add_f32 v[108:109], v[24:25], v[110:111]
	v_pk_add_f32 v[24:25], v[24:25], v[110:111] neg_lo:[0,1] neg_hi:[0,1]
	s_nop 0
	v_pk_mul_f32 v[110:111], v[24:25], s[10:11]
	s_nop 0
	v_pk_fma_f32 v[24:25], v[24:25], s[14:15], v[110:111] op_sel:[0,0,1] op_sel_hi:[1,0,0] neg_lo:[1,0,0] neg_hi:[1,0,0]
	v_pk_add_f32 v[110:111], v[26:27], v[112:113]
	v_pk_add_f32 v[26:27], v[26:27], v[112:113] neg_lo:[0,1] neg_hi:[0,1]
	s_nop 0
	v_pk_mul_f32 v[112:113], v[26:27], s[20:21]
	s_nop 0
	v_pk_fma_f32 v[26:27], v[26:27], s[86:87], v[112:113] op_sel:[0,0,1] op_sel_hi:[1,0,0] neg_lo:[1,0,0] neg_hi:[1,0,0]
	v_pk_add_f32 v[112:113], v[28:29], v[114:115]
	v_pk_add_f32 v[28:29], v[28:29], v[114:115] neg_lo:[0,1] neg_hi:[0,1]
	s_nop 0
	v_pk_mul_f32 v[114:115], v[28:29], s[18:19]
	s_nop 0
	v_pk_fma_f32 v[28:29], v[28:29], s[30:31], v[114:115] op_sel:[0,0,1] op_sel_hi:[1,0,0] neg_lo:[1,0,0] neg_hi:[1,0,0]
	s_waitcnt lgkmcnt(0)
	v_pk_add_f32 v[114:115], v[30:31], v[120:121]
	v_pk_add_f32 v[30:31], v[30:31], v[120:121] neg_lo:[0,1] neg_hi:[0,1]
	s_nop 0
	v_pk_mul_f32 v[120:121], v[30:31], s[16:17]
	s_nop 0
	v_pk_fma_f32 v[30:31], v[30:31], s[6:7], v[120:121] op_sel:[0,0,1] op_sel_hi:[1,0,0] neg_lo:[1,0,0] neg_hi:[1,0,0]
	v_pk_add_f32 v[120:121], v[124:125], v[100:101]
	v_pk_add_f32 v[100:101], v[124:125], v[100:101] neg_lo:[0,1] neg_hi:[0,1]
	v_pk_add_f32 v[124:125], v[58:59], v[102:103]
	v_pk_add_f32 v[58:59], v[58:59], v[102:103] neg_lo:[0,1] neg_hi:[0,1]
	s_nop 0
	v_pk_mul_f32 v[102:103], v[58:59], s[18:19]
	s_nop 0
	v_pk_fma_f32 v[58:59], v[58:59], s[30:31], v[102:103] op_sel:[0,0,1] op_sel_hi:[1,0,0]
	v_pk_add_f32 v[102:103], v[116:117], v[104:105]
	v_pk_add_f32 v[104:105], v[116:117], v[104:105] neg_lo:[0,1] neg_hi:[0,1]
	s_nop 0
	v_pk_mul_f32 v[116:117], v[104:105], s[10:11]
	s_nop 0
	v_pk_fma_f32 v[104:105], v[104:105], s[14:15], v[116:117] op_sel:[0,0,1] op_sel_hi:[1,0,0]
	v_pk_add_f32 v[116:117], v[118:119], v[106:107]
	v_pk_add_f32 v[106:107], v[118:119], v[106:107] neg_lo:[0,1] neg_hi:[0,1]
	s_nop 0
	v_pk_mul_f32 v[118:119], v[106:107], s[34:35]
	s_nop 0
	v_pk_fma_f32 v[106:107], v[106:107], s[8:9], v[118:119] op_sel:[0,0,1] op_sel_hi:[1,0,0]
	v_pk_add_f32 v[118:119], v[60:61], v[108:109]
	v_pk_add_f32 v[60:61], v[60:61], v[108:109] neg_lo:[0,1] neg_hi:[0,1]
	v_pk_add_f32 v[108:109], v[94:95], v[110:111]
	v_pk_add_f32 v[94:95], v[94:95], v[110:111] neg_lo:[0,1] neg_hi:[0,1]
	s_nop 0
	v_pk_mul_f32 v[110:111], v[94:95], s[34:35]
	s_nop 0
	v_pk_fma_f32 v[94:95], v[94:95], s[8:9], v[110:111] op_sel:[0,0,1] op_sel_hi:[1,0,0] neg_lo:[1,0,0] neg_hi:[1,0,0]
	v_pk_add_f32 v[110:111], v[96:97], v[112:113]
	v_pk_add_f32 v[96:97], v[96:97], v[112:113] neg_lo:[0,1] neg_hi:[0,1]
	s_nop 0
	v_pk_mul_f32 v[112:113], v[96:97], s[10:11]
	s_nop 0
	v_pk_fma_f32 v[96:97], v[96:97], s[14:15], v[112:113] op_sel:[0,0,1] op_sel_hi:[1,0,0] neg_lo:[1,0,0] neg_hi:[1,0,0]
	v_pk_add_f32 v[112:113], v[98:99], v[114:115]
	v_pk_add_f32 v[98:99], v[98:99], v[114:115] neg_lo:[0,1] neg_hi:[0,1]
	s_nop 0
	v_pk_mul_f32 v[114:115], v[98:99], s[18:19]
	s_nop 0
	v_pk_fma_f32 v[98:99], v[98:99], s[30:31], v[114:115] op_sel:[0,0,1] op_sel_hi:[1,0,0] neg_lo:[1,0,0] neg_hi:[1,0,0]
	v_pk_add_f32 v[114:115], v[0:1], v[16:17] op_sel:[0,1] op_sel_hi:[1,0] neg_hi:[0,1]
	v_pk_add_f32 v[0:1], v[0:1], v[16:17] op_sel:[0,1] op_sel_hi:[1,0] neg_lo:[0,1]
	v_pk_add_f32 v[16:17], v[2:3], v[18:19]
	v_pk_add_f32 v[2:3], v[2:3], v[18:19] neg_lo:[0,1] neg_hi:[0,1]
	s_nop 0
	v_pk_mul_f32 v[18:19], v[2:3], s[18:19]
	s_nop 0
	v_pk_fma_f32 v[2:3], v[2:3], s[30:31], v[18:19] op_sel:[0,0,1] op_sel_hi:[1,0,0]
	v_pk_add_f32 v[18:19], v[4:5], v[20:21]
	v_pk_add_f32 v[4:5], v[4:5], v[20:21] neg_lo:[0,1] neg_hi:[0,1]
	s_nop 0
	v_pk_mul_f32 v[20:21], v[4:5], s[10:11]
	s_nop 0
	v_pk_fma_f32 v[4:5], v[4:5], s[14:15], v[20:21] op_sel:[0,0,1] op_sel_hi:[1,0,0]
	v_pk_add_f32 v[20:21], v[6:7], v[22:23]
	v_pk_add_f32 v[6:7], v[6:7], v[22:23] neg_lo:[0,1] neg_hi:[0,1]
	s_nop 0
	v_pk_mul_f32 v[22:23], v[6:7], s[34:35]
	s_nop 0
	v_pk_fma_f32 v[6:7], v[6:7], s[8:9], v[22:23] op_sel:[0,0,1] op_sel_hi:[1,0,0]
	v_pk_add_f32 v[22:23], v[8:9], v[24:25]
	v_pk_add_f32 v[8:9], v[8:9], v[24:25] neg_lo:[0,1] neg_hi:[0,1]
	v_pk_add_f32 v[24:25], v[10:11], v[26:27]
	v_pk_add_f32 v[10:11], v[10:11], v[26:27] neg_lo:[0,1] neg_hi:[0,1]
	s_nop 0
	v_pk_mul_f32 v[26:27], v[10:11], s[34:35]
	s_nop 0
	v_pk_fma_f32 v[10:11], v[10:11], s[8:9], v[26:27] op_sel:[0,0,1] op_sel_hi:[1,0,0] neg_lo:[1,0,0] neg_hi:[1,0,0]
	v_pk_add_f32 v[26:27], v[12:13], v[28:29]
	v_pk_add_f32 v[12:13], v[12:13], v[28:29] neg_lo:[0,1] neg_hi:[0,1]
	s_nop 0
	v_pk_mul_f32 v[28:29], v[12:13], s[10:11]
	s_nop 0
	v_pk_fma_f32 v[12:13], v[12:13], s[14:15], v[28:29] op_sel:[0,0,1] op_sel_hi:[1,0,0] neg_lo:[1,0,0] neg_hi:[1,0,0]
	v_pk_add_f32 v[28:29], v[14:15], v[30:31]
	v_pk_add_f32 v[14:15], v[14:15], v[30:31] neg_lo:[0,1] neg_hi:[0,1]
	s_nop 0
	v_pk_mul_f32 v[30:31], v[14:15], s[18:19]
	s_nop 0
	v_pk_fma_f32 v[14:15], v[14:15], s[30:31], v[30:31] op_sel:[0,0,1] op_sel_hi:[1,0,0] neg_lo:[1,0,0] neg_hi:[1,0,0]
	v_pk_add_f32 v[30:31], v[120:121], v[118:119]
	v_pk_add_f32 v[118:119], v[120:121], v[118:119] neg_lo:[0,1] neg_hi:[0,1]
	v_pk_add_f32 v[120:121], v[124:125], v[108:109]
	v_pk_add_f32 v[108:109], v[124:125], v[108:109] neg_lo:[0,1] neg_hi:[0,1]
	s_nop 0
	v_pk_mul_f32 v[124:125], v[108:109], s[10:11]
	s_nop 0
	v_pk_fma_f32 v[108:109], v[108:109], s[14:15], v[124:125] op_sel:[0,0,1] op_sel_hi:[1,0,0]
	v_pk_add_f32 v[124:125], v[102:103], v[110:111]
	v_pk_add_f32 v[102:103], v[102:103], v[110:111] neg_lo:[0,1] neg_hi:[0,1]
	v_pk_add_f32 v[110:111], v[116:117], v[112:113]
	v_pk_add_f32 v[112:113], v[116:117], v[112:113] neg_lo:[0,1] neg_hi:[0,1]
	s_nop 0
	v_pk_mul_f32 v[116:117], v[112:113], s[10:11]
	s_nop 0
	v_pk_fma_f32 v[112:113], v[112:113], s[14:15], v[116:117] op_sel:[0,0,1] op_sel_hi:[1,0,0] neg_lo:[1,0,0] neg_hi:[1,0,0]
	v_pk_add_f32 v[116:117], v[100:101], v[60:61] op_sel:[0,1] op_sel_hi:[1,0] neg_hi:[0,1]
	v_pk_add_f32 v[60:61], v[100:101], v[60:61] op_sel:[0,1] op_sel_hi:[1,0] neg_lo:[0,1]
	v_pk_add_f32 v[100:101], v[58:59], v[94:95]
	v_pk_add_f32 v[58:59], v[58:59], v[94:95] neg_lo:[0,1] neg_hi:[0,1]
	v_pk_add_f32 v[126:127], v[108:109], v[112:113]
	v_pk_mul_f32 v[94:95], v[58:59], s[10:11]
	s_nop 0
	v_pk_fma_f32 v[58:59], v[58:59], s[14:15], v[94:95] op_sel:[0,0,1] op_sel_hi:[1,0,0]
	v_pk_add_f32 v[94:95], v[104:105], v[96:97]
	v_pk_add_f32 v[96:97], v[104:105], v[96:97] neg_lo:[0,1] neg_hi:[0,1]
	v_pk_add_f32 v[104:105], v[106:107], v[98:99]
	v_pk_add_f32 v[98:99], v[106:107], v[98:99] neg_lo:[0,1] neg_hi:[0,1]
	s_nop 0
	v_pk_mul_f32 v[106:107], v[98:99], s[10:11]
	v_pk_add_f32 v[130:131], v[60:61], v[96:97] op_sel:[0,1] op_sel_hi:[1,0] neg_hi:[0,1]
	v_pk_fma_f32 v[98:99], v[98:99], s[14:15], v[106:107] op_sel:[0,0,1] op_sel_hi:[1,0,0] neg_lo:[1,0,0] neg_hi:[1,0,0]
	v_pk_add_f32 v[106:107], v[114:115], v[22:23]
	v_pk_add_f32 v[22:23], v[114:115], v[22:23] neg_lo:[0,1] neg_hi:[0,1]
	v_pk_add_f32 v[114:115], v[16:17], v[24:25]
	v_pk_add_f32 v[16:17], v[16:17], v[24:25] neg_lo:[0,1] neg_hi:[0,1]
	v_pk_add_f32 v[132:133], v[60:61], v[96:97] op_sel:[0,1] op_sel_hi:[1,0] neg_lo:[0,1]
	v_pk_mul_f32 v[24:25], v[16:17], s[10:11]
	v_pk_add_f32 v[60:61], v[58:59], v[98:99]
	v_pk_fma_f32 v[16:17], v[16:17], s[14:15], v[24:25] op_sel:[0,0,1] op_sel_hi:[1,0,0]
	v_pk_add_f32 v[24:25], v[18:19], v[26:27]
	v_pk_add_f32 v[18:19], v[18:19], v[26:27] neg_lo:[0,1] neg_hi:[0,1]
	v_pk_add_f32 v[26:27], v[20:21], v[28:29]
	v_pk_add_f32 v[20:21], v[20:21], v[28:29] neg_lo:[0,1] neg_hi:[0,1]
	s_nop 0
	v_pk_mul_f32 v[28:29], v[20:21], s[10:11]
	v_pk_add_f32 v[58:59], v[58:59], v[98:99] neg_lo:[0,1] neg_hi:[0,1]
	v_pk_fma_f32 v[20:21], v[20:21], s[14:15], v[28:29] op_sel:[0,0,1] op_sel_hi:[1,0,0] neg_lo:[1,0,0] neg_hi:[1,0,0]
	v_pk_add_f32 v[28:29], v[0:1], v[8:9] op_sel:[0,1] op_sel_hi:[1,0] neg_hi:[0,1]
	v_pk_add_f32 v[0:1], v[0:1], v[8:9] op_sel:[0,1] op_sel_hi:[1,0] neg_lo:[0,1]
	v_pk_add_f32 v[8:9], v[2:3], v[10:11]
	v_pk_add_f32 v[2:3], v[2:3], v[10:11] neg_lo:[0,1] neg_hi:[0,1]
	v_pk_add_f32 v[134:135], v[106:107], v[24:25]
	v_pk_mul_f32 v[10:11], v[2:3], s[10:11]
	v_pk_add_f32 v[106:107], v[106:107], v[24:25] neg_lo:[0,1] neg_hi:[0,1]
	v_pk_fma_f32 v[2:3], v[2:3], s[14:15], v[10:11] op_sel:[0,0,1] op_sel_hi:[1,0,0]
	v_pk_add_f32 v[10:11], v[4:5], v[12:13]
	v_pk_add_f32 v[4:5], v[4:5], v[12:13] neg_lo:[0,1] neg_hi:[0,1]
	v_pk_add_f32 v[12:13], v[6:7], v[14:15]
	v_pk_add_f32 v[6:7], v[6:7], v[14:15] neg_lo:[0,1] neg_hi:[0,1]
	s_nop 0
	v_pk_mul_f32 v[14:15], v[6:7], s[10:11]
	v_pk_add_f32 v[24:25], v[114:115], v[26:27] neg_lo:[0,1] neg_hi:[0,1]
	v_pk_fma_f32 v[6:7], v[6:7], s[14:15], v[14:15] op_sel:[0,0,1] op_sel_hi:[1,0,0] neg_lo:[1,0,0] neg_hi:[1,0,0]
	v_pk_add_f32 v[14:15], v[30:31], v[124:125]
	v_pk_add_f32 v[30:31], v[30:31], v[124:125] neg_lo:[0,1] neg_hi:[0,1]
	v_pk_add_f32 v[124:125], v[120:121], v[110:111]
	v_pk_add_f32 v[110:111], v[120:121], v[110:111] neg_lo:[0,1] neg_hi:[0,1]
	v_pk_add_f32 v[120:121], v[118:119], v[102:103] op_sel:[0,1] op_sel_hi:[1,0] neg_hi:[0,1]
	v_pk_add_f32 v[118:119], v[118:119], v[102:103] op_sel:[0,1] op_sel_hi:[1,0] neg_lo:[0,1]
	v_pk_add_f32 v[102:103], v[108:109], v[112:113] neg_lo:[0,1] neg_hi:[0,1]
	v_pk_add_f32 v[112:113], v[116:117], v[94:95]
	v_pk_add_f32 v[94:95], v[116:117], v[94:95] neg_lo:[0,1] neg_hi:[0,1]
	v_pk_add_f32 v[116:117], v[100:101], v[104:105]
	v_pk_add_f32 v[100:101], v[100:101], v[104:105] neg_lo:[0,1] neg_hi:[0,1]
	v_pk_add_f32 v[138:139], v[22:23], v[18:19] op_sel:[0,1] op_sel_hi:[1,0] neg_hi:[0,1]
	v_pk_add_f32 v[140:141], v[22:23], v[18:19] op_sel:[0,1] op_sel_hi:[1,0] neg_lo:[0,1]
	v_pk_add_f32 v[18:19], v[16:17], v[20:21]
	v_pk_add_f32 v[16:17], v[16:17], v[20:21] neg_lo:[0,1] neg_hi:[0,1]
	v_pk_add_f32 v[144:145], v[28:29], v[10:11]
	v_pk_add_f32 v[158:159], v[28:29], v[10:11] neg_lo:[0,1] neg_hi:[0,1]
	v_pk_add_f32 v[10:11], v[8:9], v[12:13]
	v_pk_add_f32 v[8:9], v[8:9], v[12:13] neg_lo:[0,1] neg_hi:[0,1]
	v_pk_add_f32 v[162:163], v[0:1], v[4:5] op_sel:[0,1] op_sel_hi:[1,0] neg_hi:[0,1]
	v_pk_add_f32 v[164:165], v[0:1], v[4:5] op_sel:[0,1] op_sel_hi:[1,0] neg_lo:[0,1]
	v_pk_add_f32 v[0:1], v[2:3], v[6:7] neg_lo:[0,1] neg_hi:[0,1]
	v_pk_mul_f32 v[108:109], v[102:103], s[22:23]
	v_pk_mul_f32 v[128:129], v[100:101], s[22:23]
	v_pk_add_f32 v[136:137], v[114:115], v[26:27]
	v_pk_mul_f32 v[114:115], v[24:25], s[22:23]
	v_pk_mul_f32 v[142:143], v[16:17], s[22:23]
	v_pk_mul_f32 v[160:161], v[8:9], s[22:23]
	v_pk_add_f32 v[166:167], v[2:3], v[6:7]
	v_pk_mul_f32 v[168:169], v[0:1], s[22:23]
	v_pk_add_f32 v[28:29], v[14:15], v[124:125]
	v_pk_add_f32 v[104:105], v[14:15], v[124:125] neg_lo:[0,1] neg_hi:[0,1]
	v_pk_add_f32 v[24:25], v[30:31], v[110:111] op_sel:[0,1] op_sel_hi:[1,0] neg_hi:[0,1]
	v_pk_add_f32 v[102:103], v[30:31], v[110:111] op_sel:[0,1] op_sel_hi:[1,0] neg_lo:[0,1]
	v_pk_add_f32 v[20:21], v[120:121], v[126:127]
	v_pk_add_f32 v[100:101], v[120:121], v[126:127] neg_lo:[0,1] neg_hi:[0,1]
	v_pk_add_f32 v[16:17], v[118:119], v[108:109] op_sel:[0,1] op_sel_hi:[1,0]
	v_pk_add_f32 v[98:99], v[118:119], v[108:109] op_sel:[0,1] op_sel_hi:[1,0] neg_lo:[0,1] neg_hi:[0,1]
	v_pk_add_f32 v[12:13], v[112:113], v[116:117]
	v_pk_add_f32 v[96:97], v[112:113], v[116:117] neg_lo:[0,1] neg_hi:[0,1]
	v_pk_add_f32 v[8:9], v[94:95], v[128:129] op_sel:[0,1] op_sel_hi:[1,0]
	v_pk_add_f32 v[94:95], v[94:95], v[128:129] op_sel:[0,1] op_sel_hi:[1,0] neg_lo:[0,1] neg_hi:[0,1]
	v_pk_add_f32 v[4:5], v[130:131], v[60:61]
	v_pk_add_f32 v[60:61], v[130:131], v[60:61] neg_lo:[0,1] neg_hi:[0,1]
	v_pk_add_f32 v[0:1], v[132:133], v[58:59] op_sel:[0,1] op_sel_hi:[1,0] neg_hi:[0,1]
	v_pk_add_f32 v[58:59], v[132:133], v[58:59] op_sel:[0,1] op_sel_hi:[1,0] neg_lo:[0,1]
	v_pk_add_f32 v[30:31], v[134:135], v[136:137]
	v_pk_add_f32 v[120:121], v[134:135], v[136:137] neg_lo:[0,1] neg_hi:[0,1]
	v_pk_add_f32 v[26:27], v[106:107], v[114:115] op_sel:[0,1] op_sel_hi:[1,0]
	v_pk_add_f32 v[118:119], v[106:107], v[114:115] op_sel:[0,1] op_sel_hi:[1,0] neg_lo:[0,1] neg_hi:[0,1]
	v_pk_add_f32 v[22:23], v[138:139], v[18:19]
	v_pk_add_f32 v[116:117], v[138:139], v[18:19] neg_lo:[0,1] neg_hi:[0,1]
	v_pk_add_f32 v[18:19], v[140:141], v[142:143] op_sel:[0,1] op_sel_hi:[1,0]
	v_pk_add_f32 v[114:115], v[140:141], v[142:143] op_sel:[0,1] op_sel_hi:[1,0] neg_lo:[0,1] neg_hi:[0,1]
	v_pk_add_f32 v[14:15], v[144:145], v[10:11]
	v_pk_add_f32 v[112:113], v[144:145], v[10:11] neg_lo:[0,1] neg_hi:[0,1]
	v_pk_add_f32 v[10:11], v[158:159], v[160:161] op_sel:[0,1] op_sel_hi:[1,0]
	v_pk_add_f32 v[110:111], v[158:159], v[160:161] op_sel:[0,1] op_sel_hi:[1,0] neg_lo:[0,1] neg_hi:[0,1]
	v_pk_add_f32 v[6:7], v[162:163], v[166:167]
	v_pk_add_f32 v[108:109], v[162:163], v[166:167] neg_lo:[0,1] neg_hi:[0,1]
	v_pk_add_f32 v[2:3], v[164:165], v[168:169] op_sel:[0,1] op_sel_hi:[1,0]
	v_pk_add_f32 v[106:107], v[164:165], v[168:169] op_sel:[0,1] op_sel_hi:[1,0] neg_lo:[0,1] neg_hi:[0,1]
